# scan chunk 0: transition-product (P) waves run their 16-step compute at s_setprio 1 (they are the younger, longer half)
# speedup vs baseline: 1.0883x; 1.0066x over previous
; __device__ __forceinline__ void scan_rows(f32x2 (&X)[8], const ScanOps& o, const f32x4 (&b)[2], const f32x4 (&kd)[2], const f32x4 (&r)[2], const bool use_v, float& yA, float& yB) {
;     f32x2 aA = X[0] * o.kk[0].xy, aB = X[4] * o.kk[0].xy;
;     aA += X[1] * o.kk[0].zw; aB += X[5] * o.kk[0].zw;
;     aA += X[2] * o.kk[1].xy; aB += X[6] * o.kk[1].xy;
;     aA += X[3] * o.kk[1].zw; aB += X[7] * o.kk[1].zw;
;     const float saA = sum8(aA.x + aA.y), saB = sum8(aB.x + aB.y);
;     const f32x2 nA = (f32x2){-saA, -saA}, nB = (f32x2){-saB, -saB}, vA = (f32x2){o.v.x, o.v.x}, vB = (f32x2){o.v.y, o.v.y};
;     f32x2 tA, tB, accA, accB;
;     tA = X[0] * o.w[0].xy; tA += nA * b[0].xy; if (use_v) tA += vA * kd[0].xy; X[0] = tA; accA = tA * r[0].xy;
;     tB = X[4] * o.w[0].xy; tB += nB * b[0].xy; if (use_v) tB += vB * kd[0].xy; X[4] = tB; accB = tB * r[0].xy;
;     tA = X[1] * o.w[0].zw; tA += nA * b[0].zw; if (use_v) tA += vA * kd[0].zw; X[1] = tA; accA += tA * r[0].zw;
;     tB = X[5] * o.w[0].zw; tB += nB * b[0].zw; if (use_v) tB += vB * kd[0].zw; X[5] = tB; accB += tB * r[0].zw;
;     tA = X[2] * o.w[1].xy; tA += nA * b[1].xy; if (use_v) tA += vA * kd[1].xy; X[2] = tA; accA += tA * r[1].xy;
;     tB = X[6] * o.w[1].xy; tB += nB * b[1].xy; if (use_v) tB += vB * kd[1].xy; X[6] = tB; accB += tB * r[1].xy;
;     tA = X[3] * o.w[1].zw; tA += nA * b[1].zw; if (use_v) tA += vA * kd[1].zw; X[3] = tA; accA += tA * r[1].zw;
;     tB = X[7] * o.w[1].zw; tB += nB * b[1].zw; if (use_v) tB += vB * kd[1].zw; X[7] = tB; accB += tB * r[1].zw;
; __device__ void phase_scan(int c, const bf16_t* PROJ, const float* k_k, const bf16_t* Wd, const bf16_t* Bd, const float* k_a, bf16_t* Y, bf16_t* Q, float* FS, float* sm) {
;     ...
;                 for (int i = 0; i < 16; i += 2) {
;                     float yA = 0.f, yB = 0.f;
;                     scan_ld(ob, obv, i + 1, B);
;                     if (roleP) A.v = (f32x2){0.f, 0.f};
;                     scan_step1(X, A, ob + i * 64, yA, yB);
;                     *(f32x2*)(obw + i * 16 + 2 * vp) = (f32x2){yA, yB};
;                     if (i + 2 < 16) scan_ld(ob, obv, i + 2, A);
;                     if (roleP) B.v = (f32x2){0.f, 0.f};
;                     scan_step1(X, B, ob + (i + 1) * 64, yA, yB);
;                     *(f32x2*)(obw + (i + 1) * 16 + 2 * vp) = (f32x2){yA, yB};
;                 }
.Lscan_p_body:
	s_setprio 1
	ds_read_b128 v[86:89], v84 offset:0
	ds_read_b128 v[90:93], v84 offset:16
	ds_read_b128 v[94:97], v84 offset:4096
	ds_read_b128 v[98:101], v84 offset:4112
	ds_read_b128 v[102:105], v84 offset:8192
	ds_read_b128 v[106:109], v84 offset:8208
	ds_read_b128 v[118:121], v84 offset:16384
	ds_read_b128 v[122:125], v84 offset:16400
	s_waitcnt lgkmcnt(0)
	ds_read_b128 v[128:131], v84 offset:256
	ds_read_b128 v[132:135], v84 offset:272
	ds_read_b128 v[136:139], v84 offset:4352
	ds_read_b128 v[140:143], v84 offset:4368
	ds_read_b128 v[144:147], v84 offset:8448
	ds_read_b128 v[148:151], v84 offset:8464
	ds_read_b128 v[160:163], v84 offset:16640
	ds_read_b128 v[164:167], v84 offset:16656
	v_pk_mul_f32 v[212:213], v[22:23], v[94:95]
	v_pk_mul_f32 v[216:217], v[14:15], v[94:95]
	v_pk_mul_f32 v[196:197], v[22:23], v[86:87]
	v_pk_mul_f32 v[204:205], v[14:15], v[86:87]
	v_pk_fma_f32 v[212:213], v[24:25], v[96:97], v[212:213]
	v_pk_fma_f32 v[216:217], v[16:17], v[96:97], v[216:217]
	v_pk_mul_f32 v[198:199], v[24:25], v[88:89]
	v_pk_mul_f32 v[206:207], v[16:17], v[88:89]
	v_pk_fma_f32 v[212:213], v[18:19], v[98:99], v[212:213]
	v_pk_fma_f32 v[216:217], v[10:11], v[98:99], v[216:217]
	v_pk_fma_f32 v[212:213], v[20:21], v[100:101], v[212:213]
	v_pk_fma_f32 v[216:217], v[12:13], v[100:101], v[216:217]
	v_add_f32_e32 v220, v212, v213
	v_add_f32_e32 v221, v216, v217
	v_pk_mul_f32 v[200:201], v[18:19], v[90:91]
	v_pk_mul_f32 v[208:209], v[10:11], v[90:91]
	v_add_f32_dpp v220, v220, v220 quad_perm:[1,0,3,2] row_mask:0xf bank_mask:0xf bound_ctrl:1
	v_add_f32_dpp v221, v221, v221 quad_perm:[1,0,3,2] row_mask:0xf bank_mask:0xf bound_ctrl:1
	v_pk_mul_f32 v[202:203], v[20:21], v[92:93]
	v_pk_mul_f32 v[210:211], v[12:13], v[92:93]
	v_add_f32_dpp v220, v220, v220 quad_perm:[2,3,0,1] row_mask:0xf bank_mask:0xf bound_ctrl:1
	v_add_f32_dpp v221, v221, v221 quad_perm:[2,3,0,1] row_mask:0xf bank_mask:0xf bound_ctrl:1
	s_nop 0
	v_add_f32_dpp v220, v220, v220 row_half_mirror row_mask:0xf bank_mask:0xf bound_ctrl:1
	v_add_f32_dpp v221, v221, v221 row_half_mirror row_mask:0xf bank_mask:0xf bound_ctrl:1
	s_nop 0
	v_pk_fma_f32 v[22:23], v[220:221], v[102:103], v[196:197] op_sel_hi:[0,1,1] neg_lo:[1,0,0] neg_hi:[1,0,0]
	v_pk_fma_f32 v[14:15], v[220:221], v[102:103], v[204:205] op_sel:[1,0,0] op_sel_hi:[1,1,1] neg_lo:[1,0,0] neg_hi:[1,0,0]
	v_pk_fma_f32 v[24:25], v[220:221], v[104:105], v[198:199] op_sel_hi:[0,1,1] neg_lo:[1,0,0] neg_hi:[1,0,0]
	v_pk_fma_f32 v[16:17], v[220:221], v[104:105], v[206:207] op_sel:[1,0,0] op_sel_hi:[1,1,1] neg_lo:[1,0,0] neg_hi:[1,0,0]
	v_pk_fma_f32 v[18:19], v[220:221], v[106:107], v[200:201] op_sel_hi:[0,1,1] neg_lo:[1,0,0] neg_hi:[1,0,0]
	v_pk_fma_f32 v[10:11], v[220:221], v[106:107], v[208:209] op_sel:[1,0,0] op_sel_hi:[1,1,1] neg_lo:[1,0,0] neg_hi:[1,0,0]
	v_pk_fma_f32 v[20:21], v[220:221], v[108:109], v[202:203] op_sel_hi:[0,1,1] neg_lo:[1,0,0] neg_hi:[1,0,0]
	v_pk_fma_f32 v[12:13], v[220:221], v[108:109], v[210:211] op_sel:[1,0,0] op_sel_hi:[1,1,1] neg_lo:[1,0,0] neg_hi:[1,0,0]
	v_pk_mul_f32 v[222:223], v[22:23], v[118:119]
	v_pk_mul_f32 v[224:225], v[14:15], v[118:119]
	v_pk_fma_f32 v[222:223], v[24:25], v[120:121], v[222:223]
	v_pk_fma_f32 v[224:225], v[16:17], v[120:121], v[224:225]
	v_pk_fma_f32 v[222:223], v[18:19], v[122:123], v[222:223]
	v_pk_fma_f32 v[224:225], v[10:11], v[122:123], v[224:225]
	v_pk_fma_f32 v[222:223], v[20:21], v[124:125], v[222:223]
	v_pk_fma_f32 v[224:225], v[12:13], v[124:125], v[224:225]
	s_waitcnt lgkmcnt(0)
	ds_read_b128 v[86:89], v84 offset:512
	ds_read_b128 v[90:93], v84 offset:528
	ds_read_b128 v[94:97], v84 offset:4608
	ds_read_b128 v[98:101], v84 offset:4624
	ds_read_b128 v[102:105], v84 offset:8704
	ds_read_b128 v[106:109], v84 offset:8720
	ds_read_b128 v[118:121], v84 offset:16896
	ds_read_b128 v[122:125], v84 offset:16912
	v_pk_mul_f32 v[212:213], v[22:23], v[136:137]
	v_pk_mul_f32 v[216:217], v[14:15], v[136:137]
	v_pk_mul_f32 v[196:197], v[22:23], v[128:129]
	v_pk_mul_f32 v[204:205], v[14:15], v[128:129]
	v_pk_fma_f32 v[212:213], v[24:25], v[138:139], v[212:213]
	v_pk_fma_f32 v[216:217], v[16:17], v[138:139], v[216:217]
	v_pk_mul_f32 v[198:199], v[24:25], v[130:131]
	v_pk_mul_f32 v[206:207], v[16:17], v[130:131]
	v_pk_fma_f32 v[212:213], v[18:19], v[140:141], v[212:213]
	v_pk_fma_f32 v[216:217], v[10:11], v[140:141], v[216:217]
	v_pk_fma_f32 v[212:213], v[20:21], v[142:143], v[212:213]
	v_pk_fma_f32 v[216:217], v[12:13], v[142:143], v[216:217]
	v_add_f32_e32 v226, v222, v223
	v_add_f32_e32 v227, v224, v225
	v_add_f32_e32 v220, v212, v213
	v_add_f32_e32 v221, v216, v217
	v_pk_mul_f32 v[200:201], v[18:19], v[132:133]
	v_pk_mul_f32 v[208:209], v[10:11], v[132:133]
	ds_write_b64 v228, v[226:227]
	v_add_f32_dpp v220, v220, v220 quad_perm:[1,0,3,2] row_mask:0xf bank_mask:0xf bound_ctrl:1
	v_add_f32_dpp v221, v221, v221 quad_perm:[1,0,3,2] row_mask:0xf bank_mask:0xf bound_ctrl:1
	v_pk_mul_f32 v[202:203], v[20:21], v[134:135]
	v_pk_mul_f32 v[210:211], v[12:13], v[134:135]
	v_add_f32_dpp v220, v220, v220 quad_perm:[2,3,0,1] row_mask:0xf bank_mask:0xf bound_ctrl:1
	v_add_f32_dpp v221, v221, v221 quad_perm:[2,3,0,1] row_mask:0xf bank_mask:0xf bound_ctrl:1
	s_nop 0
	v_add_f32_dpp v220, v220, v220 row_half_mirror row_mask:0xf bank_mask:0xf bound_ctrl:1
	v_add_f32_dpp v221, v221, v221 row_half_mirror row_mask:0xf bank_mask:0xf bound_ctrl:1
	s_nop 0
	v_pk_fma_f32 v[22:23], v[220:221], v[144:145], v[196:197] op_sel_hi:[0,1,1] neg_lo:[1,0,0] neg_hi:[1,0,0]
	v_pk_fma_f32 v[14:15], v[220:221], v[144:145], v[204:205] op_sel:[1,0,0] op_sel_hi:[1,1,1] neg_lo:[1,0,0] neg_hi:[1,0,0]
	v_pk_fma_f32 v[24:25], v[220:221], v[146:147], v[198:199] op_sel_hi:[0,1,1] neg_lo:[1,0,0] neg_hi:[1,0,0]
	v_pk_fma_f32 v[16:17], v[220:221], v[146:147], v[206:207] op_sel:[1,0,0] op_sel_hi:[1,1,1] neg_lo:[1,0,0] neg_hi:[1,0,0]
	v_pk_fma_f32 v[18:19], v[220:221], v[148:149], v[200:201] op_sel_hi:[0,1,1] neg_lo:[1,0,0] neg_hi:[1,0,0]
	v_pk_fma_f32 v[10:11], v[220:221], v[148:149], v[208:209] op_sel:[1,0,0] op_sel_hi:[1,1,1] neg_lo:[1,0,0] neg_hi:[1,0,0]
	v_pk_fma_f32 v[20:21], v[220:221], v[150:151], v[202:203] op_sel_hi:[0,1,1] neg_lo:[1,0,0] neg_hi:[1,0,0]
	v_pk_fma_f32 v[12:13], v[220:221], v[150:151], v[210:211] op_sel:[1,0,0] op_sel_hi:[1,1,1] neg_lo:[1,0,0] neg_hi:[1,0,0]
	v_pk_mul_f32 v[222:223], v[22:23], v[160:161]
	v_pk_mul_f32 v[224:225], v[14:15], v[160:161]
	v_pk_fma_f32 v[222:223], v[24:25], v[162:163], v[222:223]
	v_pk_fma_f32 v[224:225], v[16:17], v[162:163], v[224:225]
	v_pk_fma_f32 v[222:223], v[18:19], v[164:165], v[222:223]
	v_pk_fma_f32 v[224:225], v[10:11], v[164:165], v[224:225]
	v_pk_fma_f32 v[222:223], v[20:21], v[166:167], v[222:223]
	v_pk_fma_f32 v[224:225], v[12:13], v[166:167], v[224:225]
	s_waitcnt lgkmcnt(0)
; __device__ __forceinline__ void scan_rows(f32x2 (&X)[8], const ScanOps& o, const f32x4 (&b)[2], const f32x4 (&kd)[2], const f32x4 (&r)[2], const bool use_v, float& yA, float& yB) {
;     f32x2 aA = X[0] * o.kk[0].xy, aB = X[4] * o.kk[0].xy;
;     aA += X[1] * o.kk[0].zw; aB += X[5] * o.kk[0].zw;
;     aA += X[2] * o.kk[1].xy; aB += X[6] * o.kk[1].xy;
;     aA += X[3] * o.kk[1].zw; aB += X[7] * o.kk[1].zw;
;     const float saA = sum8(aA.x + aA.y), saB = sum8(aB.x + aB.y);
;     const f32x2 nA = (f32x2){-saA, -saA}, nB = (f32x2){-saB, -saB}, vA = (f32x2){o.v.x, o.v.x}, vB = (f32x2){o.v.y, o.v.y};
;     f32x2 tA, tB, accA, accB;
;     tA = X[0] * o.w[0].xy; tA += nA * b[0].xy; if (use_v) tA += vA * kd[0].xy; X[0] = tA; accA = tA * r[0].xy;
;     tB = X[4] * o.w[0].xy; tB += nB * b[0].xy; if (use_v) tB += vB * kd[0].xy; X[4] = tB; accB = tB * r[0].xy;
;     tA = X[1] * o.w[0].zw; tA += nA * b[0].zw; if (use_v) tA += vA * kd[0].zw; X[1] = tA; accA += tA * r[0].zw;
;     tB = X[5] * o.w[0].zw; tB += nB * b[0].zw; if (use_v) tB += vB * kd[0].zw; X[5] = tB; accB += tB * r[0].zw;
;     tA = X[2] * o.w[1].xy; tA += nA * b[1].xy; if (use_v) tA += vA * kd[1].xy; X[2] = tA; accA += tA * r[1].xy;
;     tB = X[6] * o.w[1].xy; tB += nB * b[1].xy; if (use_v) tB += vB * kd[1].xy; X[6] = tB; accB += tB * r[1].xy;
;     tA = X[3] * o.w[1].zw; tA += nA * b[1].zw; if (use_v) tA += vA * kd[1].zw; X[3] = tA; accA += tA * r[1].zw;
;     tB = X[7] * o.w[1].zw; tB += nB * b[1].zw; if (use_v) tB += vB * kd[1].zw; X[7] = tB; accB += tB * r[1].zw;
; __device__ void phase_scan(int c, const bf16_t* PROJ, const float* k_k, const bf16_t* Wd, const bf16_t* Bd, const float* k_a, bf16_t* Y, bf16_t* Q, float* FS, float* sm) {
;     ...
;                 for (int i = 0; i < 16; i += 2) {
;                     float yA = 0.f, yB = 0.f;
;                     scan_ld(ob, obv, i + 1, B);
;                     if (roleP) A.v = (f32x2){0.f, 0.f};
;                     scan_step1(X, A, ob + i * 64, yA, yB);
;                     *(f32x2*)(obw + i * 16 + 2 * vp) = (f32x2){yA, yB};
;                     if (i + 2 < 16) scan_ld(ob, obv, i + 2, A);
;                     if (roleP) B.v = (f32x2){0.f, 0.f};
;                     scan_step1(X, B, ob + (i + 1) * 64, yA, yB);
;                     *(f32x2*)(obw + (i + 1) * 16 + 2 * vp) = (f32x2){yA, yB};
;                 }
	ds_read_b128 v[128:131], v84 offset:768
	ds_read_b128 v[132:135], v84 offset:784
	ds_read_b128 v[136:139], v84 offset:4864
	ds_read_b128 v[140:143], v84 offset:4880
	ds_read_b128 v[144:147], v84 offset:8960
	ds_read_b128 v[148:151], v84 offset:8976
	ds_read_b128 v[160:163], v84 offset:17152
	ds_read_b128 v[164:167], v84 offset:17168
	v_pk_mul_f32 v[212:213], v[22:23], v[94:95]
	v_pk_mul_f32 v[216:217], v[14:15], v[94:95]
	v_pk_mul_f32 v[196:197], v[22:23], v[86:87]
	v_pk_mul_f32 v[204:205], v[14:15], v[86:87]
	v_pk_fma_f32 v[212:213], v[24:25], v[96:97], v[212:213]
	v_pk_fma_f32 v[216:217], v[16:17], v[96:97], v[216:217]
	v_pk_mul_f32 v[198:199], v[24:25], v[88:89]
	v_pk_mul_f32 v[206:207], v[16:17], v[88:89]
	v_pk_fma_f32 v[212:213], v[18:19], v[98:99], v[212:213]
	v_pk_fma_f32 v[216:217], v[10:11], v[98:99], v[216:217]
	v_pk_fma_f32 v[212:213], v[20:21], v[100:101], v[212:213]
	v_pk_fma_f32 v[216:217], v[12:13], v[100:101], v[216:217]
	v_add_f32_e32 v226, v222, v223
	v_add_f32_e32 v227, v224, v225
	v_add_f32_e32 v220, v212, v213
	v_add_f32_e32 v221, v216, v217
	v_pk_mul_f32 v[200:201], v[18:19], v[90:91]
	v_pk_mul_f32 v[208:209], v[10:11], v[90:91]
	ds_write_b64 v228, v[226:227] offset:576
	v_add_f32_dpp v220, v220, v220 quad_perm:[1,0,3,2] row_mask:0xf bank_mask:0xf bound_ctrl:1
	v_add_f32_dpp v221, v221, v221 quad_perm:[1,0,3,2] row_mask:0xf bank_mask:0xf bound_ctrl:1
	v_pk_mul_f32 v[202:203], v[20:21], v[92:93]
	v_pk_mul_f32 v[210:211], v[12:13], v[92:93]
	v_add_f32_dpp v220, v220, v220 quad_perm:[2,3,0,1] row_mask:0xf bank_mask:0xf bound_ctrl:1
	v_add_f32_dpp v221, v221, v221 quad_perm:[2,3,0,1] row_mask:0xf bank_mask:0xf bound_ctrl:1
	s_nop 0
	v_add_f32_dpp v220, v220, v220 row_half_mirror row_mask:0xf bank_mask:0xf bound_ctrl:1
	v_add_f32_dpp v221, v221, v221 row_half_mirror row_mask:0xf bank_mask:0xf bound_ctrl:1
	s_nop 0
	v_pk_fma_f32 v[22:23], v[220:221], v[102:103], v[196:197] op_sel_hi:[0,1,1] neg_lo:[1,0,0] neg_hi:[1,0,0]
	v_pk_fma_f32 v[14:15], v[220:221], v[102:103], v[204:205] op_sel:[1,0,0] op_sel_hi:[1,1,1] neg_lo:[1,0,0] neg_hi:[1,0,0]
	v_pk_fma_f32 v[24:25], v[220:221], v[104:105], v[198:199] op_sel_hi:[0,1,1] neg_lo:[1,0,0] neg_hi:[1,0,0]
	v_pk_fma_f32 v[16:17], v[220:221], v[104:105], v[206:207] op_sel:[1,0,0] op_sel_hi:[1,1,1] neg_lo:[1,0,0] neg_hi:[1,0,0]
	v_pk_fma_f32 v[18:19], v[220:221], v[106:107], v[200:201] op_sel_hi:[0,1,1] neg_lo:[1,0,0] neg_hi:[1,0,0]
	v_pk_fma_f32 v[10:11], v[220:221], v[106:107], v[208:209] op_sel:[1,0,0] op_sel_hi:[1,1,1] neg_lo:[1,0,0] neg_hi:[1,0,0]
	v_pk_fma_f32 v[20:21], v[220:221], v[108:109], v[202:203] op_sel_hi:[0,1,1] neg_lo:[1,0,0] neg_hi:[1,0,0]
	v_pk_fma_f32 v[12:13], v[220:221], v[108:109], v[210:211] op_sel:[1,0,0] op_sel_hi:[1,1,1] neg_lo:[1,0,0] neg_hi:[1,0,0]
	v_pk_mul_f32 v[222:223], v[22:23], v[118:119]
	v_pk_mul_f32 v[224:225], v[14:15], v[118:119]
	v_pk_fma_f32 v[222:223], v[24:25], v[120:121], v[222:223]
	v_pk_fma_f32 v[224:225], v[16:17], v[120:121], v[224:225]
	v_pk_fma_f32 v[222:223], v[18:19], v[122:123], v[222:223]
	v_pk_fma_f32 v[224:225], v[10:11], v[122:123], v[224:225]
	v_pk_fma_f32 v[222:223], v[20:21], v[124:125], v[222:223]
	v_pk_fma_f32 v[224:225], v[12:13], v[124:125], v[224:225]
	s_waitcnt lgkmcnt(0)
	ds_read_b128 v[86:89], v84 offset:1024
	ds_read_b128 v[90:93], v84 offset:1040
	ds_read_b128 v[94:97], v84 offset:5120
	ds_read_b128 v[98:101], v84 offset:5136
	ds_read_b128 v[102:105], v84 offset:9216
	ds_read_b128 v[106:109], v84 offset:9232
	ds_read_b128 v[118:121], v84 offset:17408
	ds_read_b128 v[122:125], v84 offset:17424
	v_pk_mul_f32 v[212:213], v[22:23], v[136:137]
	v_pk_mul_f32 v[216:217], v[14:15], v[136:137]
	v_pk_mul_f32 v[196:197], v[22:23], v[128:129]
	v_pk_mul_f32 v[204:205], v[14:15], v[128:129]
	v_pk_fma_f32 v[212:213], v[24:25], v[138:139], v[212:213]
	v_pk_fma_f32 v[216:217], v[16:17], v[138:139], v[216:217]
	v_pk_mul_f32 v[198:199], v[24:25], v[130:131]
	v_pk_mul_f32 v[206:207], v[16:17], v[130:131]
	v_pk_fma_f32 v[212:213], v[18:19], v[140:141], v[212:213]
	v_pk_fma_f32 v[216:217], v[10:11], v[140:141], v[216:217]
	v_pk_fma_f32 v[212:213], v[20:21], v[142:143], v[212:213]
	v_pk_fma_f32 v[216:217], v[12:13], v[142:143], v[216:217]
	v_add_f32_e32 v226, v222, v223
	v_add_f32_e32 v227, v224, v225
	v_add_f32_e32 v220, v212, v213
	v_add_f32_e32 v221, v216, v217
	v_pk_mul_f32 v[200:201], v[18:19], v[132:133]
	v_pk_mul_f32 v[208:209], v[10:11], v[132:133]
	ds_write_b64 v228, v[226:227] offset:1152
	v_add_f32_dpp v220, v220, v220 quad_perm:[1,0,3,2] row_mask:0xf bank_mask:0xf bound_ctrl:1
	v_add_f32_dpp v221, v221, v221 quad_perm:[1,0,3,2] row_mask:0xf bank_mask:0xf bound_ctrl:1
	v_pk_mul_f32 v[202:203], v[20:21], v[134:135]
	v_pk_mul_f32 v[210:211], v[12:13], v[134:135]
	v_add_f32_dpp v220, v220, v220 quad_perm:[2,3,0,1] row_mask:0xf bank_mask:0xf bound_ctrl:1
	v_add_f32_dpp v221, v221, v221 quad_perm:[2,3,0,1] row_mask:0xf bank_mask:0xf bound_ctrl:1
	s_nop 0
	v_add_f32_dpp v220, v220, v220 row_half_mirror row_mask:0xf bank_mask:0xf bound_ctrl:1
	v_add_f32_dpp v221, v221, v221 row_half_mirror row_mask:0xf bank_mask:0xf bound_ctrl:1
	s_nop 0
	v_pk_fma_f32 v[22:23], v[220:221], v[144:145], v[196:197] op_sel_hi:[0,1,1] neg_lo:[1,0,0] neg_hi:[1,0,0]
	v_pk_fma_f32 v[14:15], v[220:221], v[144:145], v[204:205] op_sel:[1,0,0] op_sel_hi:[1,1,1] neg_lo:[1,0,0] neg_hi:[1,0,0]
	v_pk_fma_f32 v[24:25], v[220:221], v[146:147], v[198:199] op_sel_hi:[0,1,1] neg_lo:[1,0,0] neg_hi:[1,0,0]
	v_pk_fma_f32 v[16:17], v[220:221], v[146:147], v[206:207] op_sel:[1,0,0] op_sel_hi:[1,1,1] neg_lo:[1,0,0] neg_hi:[1,0,0]
	v_pk_fma_f32 v[18:19], v[220:221], v[148:149], v[200:201] op_sel_hi:[0,1,1] neg_lo:[1,0,0] neg_hi:[1,0,0]
	v_pk_fma_f32 v[10:11], v[220:221], v[148:149], v[208:209] op_sel:[1,0,0] op_sel_hi:[1,1,1] neg_lo:[1,0,0] neg_hi:[1,0,0]
	v_pk_fma_f32 v[20:21], v[220:221], v[150:151], v[202:203] op_sel_hi:[0,1,1] neg_lo:[1,0,0] neg_hi:[1,0,0]
	v_pk_fma_f32 v[12:13], v[220:221], v[150:151], v[210:211] op_sel:[1,0,0] op_sel_hi:[1,1,1] neg_lo:[1,0,0] neg_hi:[1,0,0]
	v_pk_mul_f32 v[222:223], v[22:23], v[160:161]
	v_pk_mul_f32 v[224:225], v[14:15], v[160:161]
	v_pk_fma_f32 v[222:223], v[24:25], v[162:163], v[222:223]
	v_pk_fma_f32 v[224:225], v[16:17], v[162:163], v[224:225]
	v_pk_fma_f32 v[222:223], v[18:19], v[164:165], v[222:223]
	v_pk_fma_f32 v[224:225], v[10:11], v[164:165], v[224:225]
	v_pk_fma_f32 v[222:223], v[20:21], v[166:167], v[222:223]
	v_pk_fma_f32 v[224:225], v[12:13], v[166:167], v[224:225]
	s_waitcnt lgkmcnt(0)
; __device__ __forceinline__ void scan_rows(f32x2 (&X)[8], const ScanOps& o, const f32x4 (&b)[2], const f32x4 (&kd)[2], const f32x4 (&r)[2], const bool use_v, float& yA, float& yB) {
;     f32x2 aA = X[0] * o.kk[0].xy, aB = X[4] * o.kk[0].xy;
;     aA += X[1] * o.kk[0].zw; aB += X[5] * o.kk[0].zw;
;     aA += X[2] * o.kk[1].xy; aB += X[6] * o.kk[1].xy;
;     aA += X[3] * o.kk[1].zw; aB += X[7] * o.kk[1].zw;
;     const float saA = sum8(aA.x + aA.y), saB = sum8(aB.x + aB.y);
;     const f32x2 nA = (f32x2){-saA, -saA}, nB = (f32x2){-saB, -saB}, vA = (f32x2){o.v.x, o.v.x}, vB = (f32x2){o.v.y, o.v.y};
;     f32x2 tA, tB, accA, accB;
;     tA = X[0] * o.w[0].xy; tA += nA * b[0].xy; if (use_v) tA += vA * kd[0].xy; X[0] = tA; accA = tA * r[0].xy;
;     tB = X[4] * o.w[0].xy; tB += nB * b[0].xy; if (use_v) tB += vB * kd[0].xy; X[4] = tB; accB = tB * r[0].xy;
;     tA = X[1] * o.w[0].zw; tA += nA * b[0].zw; if (use_v) tA += vA * kd[0].zw; X[1] = tA; accA += tA * r[0].zw;
;     tB = X[5] * o.w[0].zw; tB += nB * b[0].zw; if (use_v) tB += vB * kd[0].zw; X[5] = tB; accB += tB * r[0].zw;
;     tA = X[2] * o.w[1].xy; tA += nA * b[1].xy; if (use_v) tA += vA * kd[1].xy; X[2] = tA; accA += tA * r[1].xy;
;     tB = X[6] * o.w[1].xy; tB += nB * b[1].xy; if (use_v) tB += vB * kd[1].xy; X[6] = tB; accB += tB * r[1].xy;
;     tA = X[3] * o.w[1].zw; tA += nA * b[1].zw; if (use_v) tA += vA * kd[1].zw; X[3] = tA; accA += tA * r[1].zw;
;     tB = X[7] * o.w[1].zw; tB += nB * b[1].zw; if (use_v) tB += vB * kd[1].zw; X[7] = tB; accB += tB * r[1].zw;
; __device__ void phase_scan(int c, const bf16_t* PROJ, const float* k_k, const bf16_t* Wd, const bf16_t* Bd, const float* k_a, bf16_t* Y, bf16_t* Q, float* FS, float* sm) {
;     ...
;                 for (int i = 0; i < 16; i += 2) {
;                     float yA = 0.f, yB = 0.f;
;                     scan_ld(ob, obv, i + 1, B);
;                     if (roleP) A.v = (f32x2){0.f, 0.f};
;                     scan_step1(X, A, ob + i * 64, yA, yB);
;                     *(f32x2*)(obw + i * 16 + 2 * vp) = (f32x2){yA, yB};
;                     if (i + 2 < 16) scan_ld(ob, obv, i + 2, A);
;                     if (roleP) B.v = (f32x2){0.f, 0.f};
;                     scan_step1(X, B, ob + (i + 1) * 64, yA, yB);
;                     *(f32x2*)(obw + (i + 1) * 16 + 2 * vp) = (f32x2){yA, yB};
;                 }
	ds_read_b128 v[128:131], v84 offset:1280
	ds_read_b128 v[132:135], v84 offset:1296
	ds_read_b128 v[136:139], v84 offset:5376
	ds_read_b128 v[140:143], v84 offset:5392
	ds_read_b128 v[144:147], v84 offset:9472
	ds_read_b128 v[148:151], v84 offset:9488
	ds_read_b128 v[160:163], v84 offset:17664
	ds_read_b128 v[164:167], v84 offset:17680
	v_pk_mul_f32 v[212:213], v[22:23], v[94:95]
	v_pk_mul_f32 v[216:217], v[14:15], v[94:95]
	v_pk_mul_f32 v[196:197], v[22:23], v[86:87]
	v_pk_mul_f32 v[204:205], v[14:15], v[86:87]
	v_pk_fma_f32 v[212:213], v[24:25], v[96:97], v[212:213]
	v_pk_fma_f32 v[216:217], v[16:17], v[96:97], v[216:217]
	v_pk_mul_f32 v[198:199], v[24:25], v[88:89]
	v_pk_mul_f32 v[206:207], v[16:17], v[88:89]
	v_pk_fma_f32 v[212:213], v[18:19], v[98:99], v[212:213]
	v_pk_fma_f32 v[216:217], v[10:11], v[98:99], v[216:217]
	v_pk_fma_f32 v[212:213], v[20:21], v[100:101], v[212:213]
	v_pk_fma_f32 v[216:217], v[12:13], v[100:101], v[216:217]
	v_add_f32_e32 v226, v222, v223
	v_add_f32_e32 v227, v224, v225
	v_add_f32_e32 v220, v212, v213
	v_add_f32_e32 v221, v216, v217
	v_pk_mul_f32 v[200:201], v[18:19], v[90:91]
	v_pk_mul_f32 v[208:209], v[10:11], v[90:91]
	ds_write_b64 v228, v[226:227] offset:1728
	v_add_f32_dpp v220, v220, v220 quad_perm:[1,0,3,2] row_mask:0xf bank_mask:0xf bound_ctrl:1
	v_add_f32_dpp v221, v221, v221 quad_perm:[1,0,3,2] row_mask:0xf bank_mask:0xf bound_ctrl:1
	v_pk_mul_f32 v[202:203], v[20:21], v[92:93]
	v_pk_mul_f32 v[210:211], v[12:13], v[92:93]
	v_add_f32_dpp v220, v220, v220 quad_perm:[2,3,0,1] row_mask:0xf bank_mask:0xf bound_ctrl:1
	v_add_f32_dpp v221, v221, v221 quad_perm:[2,3,0,1] row_mask:0xf bank_mask:0xf bound_ctrl:1
	s_nop 0
	v_add_f32_dpp v220, v220, v220 row_half_mirror row_mask:0xf bank_mask:0xf bound_ctrl:1
	v_add_f32_dpp v221, v221, v221 row_half_mirror row_mask:0xf bank_mask:0xf bound_ctrl:1
	s_nop 0
	v_pk_fma_f32 v[22:23], v[220:221], v[102:103], v[196:197] op_sel_hi:[0,1,1] neg_lo:[1,0,0] neg_hi:[1,0,0]
	v_pk_fma_f32 v[14:15], v[220:221], v[102:103], v[204:205] op_sel:[1,0,0] op_sel_hi:[1,1,1] neg_lo:[1,0,0] neg_hi:[1,0,0]
	v_pk_fma_f32 v[24:25], v[220:221], v[104:105], v[198:199] op_sel_hi:[0,1,1] neg_lo:[1,0,0] neg_hi:[1,0,0]
	v_pk_fma_f32 v[16:17], v[220:221], v[104:105], v[206:207] op_sel:[1,0,0] op_sel_hi:[1,1,1] neg_lo:[1,0,0] neg_hi:[1,0,0]
	v_pk_fma_f32 v[18:19], v[220:221], v[106:107], v[200:201] op_sel_hi:[0,1,1] neg_lo:[1,0,0] neg_hi:[1,0,0]
	v_pk_fma_f32 v[10:11], v[220:221], v[106:107], v[208:209] op_sel:[1,0,0] op_sel_hi:[1,1,1] neg_lo:[1,0,0] neg_hi:[1,0,0]
	v_pk_fma_f32 v[20:21], v[220:221], v[108:109], v[202:203] op_sel_hi:[0,1,1] neg_lo:[1,0,0] neg_hi:[1,0,0]
	v_pk_fma_f32 v[12:13], v[220:221], v[108:109], v[210:211] op_sel:[1,0,0] op_sel_hi:[1,1,1] neg_lo:[1,0,0] neg_hi:[1,0,0]
	v_pk_mul_f32 v[222:223], v[22:23], v[118:119]
	v_pk_mul_f32 v[224:225], v[14:15], v[118:119]
	v_pk_fma_f32 v[222:223], v[24:25], v[120:121], v[222:223]
	v_pk_fma_f32 v[224:225], v[16:17], v[120:121], v[224:225]
	v_pk_fma_f32 v[222:223], v[18:19], v[122:123], v[222:223]
	v_pk_fma_f32 v[224:225], v[10:11], v[122:123], v[224:225]
	v_pk_fma_f32 v[222:223], v[20:21], v[124:125], v[222:223]
	v_pk_fma_f32 v[224:225], v[12:13], v[124:125], v[224:225]
	s_waitcnt lgkmcnt(0)
	ds_read_b128 v[86:89], v84 offset:1536
	ds_read_b128 v[90:93], v84 offset:1552
	ds_read_b128 v[94:97], v84 offset:5632
	ds_read_b128 v[98:101], v84 offset:5648
	ds_read_b128 v[102:105], v84 offset:9728
	ds_read_b128 v[106:109], v84 offset:9744
	ds_read_b128 v[118:121], v84 offset:17920
	ds_read_b128 v[122:125], v84 offset:17936
	v_pk_mul_f32 v[212:213], v[22:23], v[136:137]
	v_pk_mul_f32 v[216:217], v[14:15], v[136:137]
	v_pk_mul_f32 v[196:197], v[22:23], v[128:129]
	v_pk_mul_f32 v[204:205], v[14:15], v[128:129]
	v_pk_fma_f32 v[212:213], v[24:25], v[138:139], v[212:213]
	v_pk_fma_f32 v[216:217], v[16:17], v[138:139], v[216:217]
	v_pk_mul_f32 v[198:199], v[24:25], v[130:131]
	v_pk_mul_f32 v[206:207], v[16:17], v[130:131]
	v_pk_fma_f32 v[212:213], v[18:19], v[140:141], v[212:213]
	v_pk_fma_f32 v[216:217], v[10:11], v[140:141], v[216:217]
	v_pk_fma_f32 v[212:213], v[20:21], v[142:143], v[212:213]
	v_pk_fma_f32 v[216:217], v[12:13], v[142:143], v[216:217]
	v_add_f32_e32 v226, v222, v223
	v_add_f32_e32 v227, v224, v225
	v_add_f32_e32 v220, v212, v213
	v_add_f32_e32 v221, v216, v217
	v_pk_mul_f32 v[200:201], v[18:19], v[132:133]
	v_pk_mul_f32 v[208:209], v[10:11], v[132:133]
	ds_write_b64 v228, v[226:227] offset:2304
	v_add_f32_dpp v220, v220, v220 quad_perm:[1,0,3,2] row_mask:0xf bank_mask:0xf bound_ctrl:1
	v_add_f32_dpp v221, v221, v221 quad_perm:[1,0,3,2] row_mask:0xf bank_mask:0xf bound_ctrl:1
	v_pk_mul_f32 v[202:203], v[20:21], v[134:135]
	v_pk_mul_f32 v[210:211], v[12:13], v[134:135]
	v_add_f32_dpp v220, v220, v220 quad_perm:[2,3,0,1] row_mask:0xf bank_mask:0xf bound_ctrl:1
	v_add_f32_dpp v221, v221, v221 quad_perm:[2,3,0,1] row_mask:0xf bank_mask:0xf bound_ctrl:1
	s_nop 0
	v_add_f32_dpp v220, v220, v220 row_half_mirror row_mask:0xf bank_mask:0xf bound_ctrl:1
	v_add_f32_dpp v221, v221, v221 row_half_mirror row_mask:0xf bank_mask:0xf bound_ctrl:1
	s_nop 0
	v_pk_fma_f32 v[22:23], v[220:221], v[144:145], v[196:197] op_sel_hi:[0,1,1] neg_lo:[1,0,0] neg_hi:[1,0,0]
	v_pk_fma_f32 v[14:15], v[220:221], v[144:145], v[204:205] op_sel:[1,0,0] op_sel_hi:[1,1,1] neg_lo:[1,0,0] neg_hi:[1,0,0]
	v_pk_fma_f32 v[24:25], v[220:221], v[146:147], v[198:199] op_sel_hi:[0,1,1] neg_lo:[1,0,0] neg_hi:[1,0,0]
	v_pk_fma_f32 v[16:17], v[220:221], v[146:147], v[206:207] op_sel:[1,0,0] op_sel_hi:[1,1,1] neg_lo:[1,0,0] neg_hi:[1,0,0]
	v_pk_fma_f32 v[18:19], v[220:221], v[148:149], v[200:201] op_sel_hi:[0,1,1] neg_lo:[1,0,0] neg_hi:[1,0,0]
	v_pk_fma_f32 v[10:11], v[220:221], v[148:149], v[208:209] op_sel:[1,0,0] op_sel_hi:[1,1,1] neg_lo:[1,0,0] neg_hi:[1,0,0]
	v_pk_fma_f32 v[20:21], v[220:221], v[150:151], v[202:203] op_sel_hi:[0,1,1] neg_lo:[1,0,0] neg_hi:[1,0,0]
	v_pk_fma_f32 v[12:13], v[220:221], v[150:151], v[210:211] op_sel:[1,0,0] op_sel_hi:[1,1,1] neg_lo:[1,0,0] neg_hi:[1,0,0]
	v_pk_mul_f32 v[222:223], v[22:23], v[160:161]
	v_pk_mul_f32 v[224:225], v[14:15], v[160:161]
	v_pk_fma_f32 v[222:223], v[24:25], v[162:163], v[222:223]
	v_pk_fma_f32 v[224:225], v[16:17], v[162:163], v[224:225]
	v_pk_fma_f32 v[222:223], v[18:19], v[164:165], v[222:223]
	v_pk_fma_f32 v[224:225], v[10:11], v[164:165], v[224:225]
	v_pk_fma_f32 v[222:223], v[20:21], v[166:167], v[222:223]
	v_pk_fma_f32 v[224:225], v[12:13], v[166:167], v[224:225]
	s_waitcnt lgkmcnt(0)
; __device__ __forceinline__ void scan_rows(f32x2 (&X)[8], const ScanOps& o, const f32x4 (&b)[2], const f32x4 (&kd)[2], const f32x4 (&r)[2], const bool use_v, float& yA, float& yB) {
;     f32x2 aA = X[0] * o.kk[0].xy, aB = X[4] * o.kk[0].xy;
;     aA += X[1] * o.kk[0].zw; aB += X[5] * o.kk[0].zw;
;     aA += X[2] * o.kk[1].xy; aB += X[6] * o.kk[1].xy;
;     aA += X[3] * o.kk[1].zw; aB += X[7] * o.kk[1].zw;
;     const float saA = sum8(aA.x + aA.y), saB = sum8(aB.x + aB.y);
;     const f32x2 nA = (f32x2){-saA, -saA}, nB = (f32x2){-saB, -saB}, vA = (f32x2){o.v.x, o.v.x}, vB = (f32x2){o.v.y, o.v.y};
;     f32x2 tA, tB, accA, accB;
;     tA = X[0] * o.w[0].xy; tA += nA * b[0].xy; if (use_v) tA += vA * kd[0].xy; X[0] = tA; accA = tA * r[0].xy;
;     tB = X[4] * o.w[0].xy; tB += nB * b[0].xy; if (use_v) tB += vB * kd[0].xy; X[4] = tB; accB = tB * r[0].xy;
;     tA = X[1] * o.w[0].zw; tA += nA * b[0].zw; if (use_v) tA += vA * kd[0].zw; X[1] = tA; accA += tA * r[0].zw;
;     tB = X[5] * o.w[0].zw; tB += nB * b[0].zw; if (use_v) tB += vB * kd[0].zw; X[5] = tB; accB += tB * r[0].zw;
;     tA = X[2] * o.w[1].xy; tA += nA * b[1].xy; if (use_v) tA += vA * kd[1].xy; X[2] = tA; accA += tA * r[1].xy;
;     tB = X[6] * o.w[1].xy; tB += nB * b[1].xy; if (use_v) tB += vB * kd[1].xy; X[6] = tB; accB += tB * r[1].xy;
;     tA = X[3] * o.w[1].zw; tA += nA * b[1].zw; if (use_v) tA += vA * kd[1].zw; X[3] = tA; accA += tA * r[1].zw;
;     tB = X[7] * o.w[1].zw; tB += nB * b[1].zw; if (use_v) tB += vB * kd[1].zw; X[7] = tB; accB += tB * r[1].zw;
; __device__ void phase_scan(int c, const bf16_t* PROJ, const float* k_k, const bf16_t* Wd, const bf16_t* Bd, const float* k_a, bf16_t* Y, bf16_t* Q, float* FS, float* sm) {
;     ...
;                 for (int i = 0; i < 16; i += 2) {
;                     float yA = 0.f, yB = 0.f;
;                     scan_ld(ob, obv, i + 1, B);
;                     if (roleP) A.v = (f32x2){0.f, 0.f};
;                     scan_step1(X, A, ob + i * 64, yA, yB);
;                     *(f32x2*)(obw + i * 16 + 2 * vp) = (f32x2){yA, yB};
;                     if (i + 2 < 16) scan_ld(ob, obv, i + 2, A);
;                     if (roleP) B.v = (f32x2){0.f, 0.f};
;                     scan_step1(X, B, ob + (i + 1) * 64, yA, yB);
;                     *(f32x2*)(obw + (i + 1) * 16 + 2 * vp) = (f32x2){yA, yB};
;                 }
	ds_read_b128 v[128:131], v84 offset:1792
	ds_read_b128 v[132:135], v84 offset:1808
	ds_read_b128 v[136:139], v84 offset:5888
	ds_read_b128 v[140:143], v84 offset:5904
	ds_read_b128 v[144:147], v84 offset:9984
	ds_read_b128 v[148:151], v84 offset:10000
	ds_read_b128 v[160:163], v84 offset:18176
	ds_read_b128 v[164:167], v84 offset:18192
	v_pk_mul_f32 v[212:213], v[22:23], v[94:95]
	v_pk_mul_f32 v[216:217], v[14:15], v[94:95]
	v_pk_mul_f32 v[196:197], v[22:23], v[86:87]
	v_pk_mul_f32 v[204:205], v[14:15], v[86:87]
	v_pk_fma_f32 v[212:213], v[24:25], v[96:97], v[212:213]
	v_pk_fma_f32 v[216:217], v[16:17], v[96:97], v[216:217]
	v_pk_mul_f32 v[198:199], v[24:25], v[88:89]
	v_pk_mul_f32 v[206:207], v[16:17], v[88:89]
	v_pk_fma_f32 v[212:213], v[18:19], v[98:99], v[212:213]
	v_pk_fma_f32 v[216:217], v[10:11], v[98:99], v[216:217]
	v_pk_fma_f32 v[212:213], v[20:21], v[100:101], v[212:213]
	v_pk_fma_f32 v[216:217], v[12:13], v[100:101], v[216:217]
	v_add_f32_e32 v226, v222, v223
	v_add_f32_e32 v227, v224, v225
	v_add_f32_e32 v220, v212, v213
	v_add_f32_e32 v221, v216, v217
	v_pk_mul_f32 v[200:201], v[18:19], v[90:91]
	v_pk_mul_f32 v[208:209], v[10:11], v[90:91]
	ds_write_b64 v228, v[226:227] offset:2880
	v_add_f32_dpp v220, v220, v220 quad_perm:[1,0,3,2] row_mask:0xf bank_mask:0xf bound_ctrl:1
	v_add_f32_dpp v221, v221, v221 quad_perm:[1,0,3,2] row_mask:0xf bank_mask:0xf bound_ctrl:1
	v_pk_mul_f32 v[202:203], v[20:21], v[92:93]
	v_pk_mul_f32 v[210:211], v[12:13], v[92:93]
	v_add_f32_dpp v220, v220, v220 quad_perm:[2,3,0,1] row_mask:0xf bank_mask:0xf bound_ctrl:1
	v_add_f32_dpp v221, v221, v221 quad_perm:[2,3,0,1] row_mask:0xf bank_mask:0xf bound_ctrl:1
	s_nop 0
	v_add_f32_dpp v220, v220, v220 row_half_mirror row_mask:0xf bank_mask:0xf bound_ctrl:1
	v_add_f32_dpp v221, v221, v221 row_half_mirror row_mask:0xf bank_mask:0xf bound_ctrl:1
	s_nop 0
	v_pk_fma_f32 v[22:23], v[220:221], v[102:103], v[196:197] op_sel_hi:[0,1,1] neg_lo:[1,0,0] neg_hi:[1,0,0]
	v_pk_fma_f32 v[14:15], v[220:221], v[102:103], v[204:205] op_sel:[1,0,0] op_sel_hi:[1,1,1] neg_lo:[1,0,0] neg_hi:[1,0,0]
	v_pk_fma_f32 v[24:25], v[220:221], v[104:105], v[198:199] op_sel_hi:[0,1,1] neg_lo:[1,0,0] neg_hi:[1,0,0]
	v_pk_fma_f32 v[16:17], v[220:221], v[104:105], v[206:207] op_sel:[1,0,0] op_sel_hi:[1,1,1] neg_lo:[1,0,0] neg_hi:[1,0,0]
	v_pk_fma_f32 v[18:19], v[220:221], v[106:107], v[200:201] op_sel_hi:[0,1,1] neg_lo:[1,0,0] neg_hi:[1,0,0]
	v_pk_fma_f32 v[10:11], v[220:221], v[106:107], v[208:209] op_sel:[1,0,0] op_sel_hi:[1,1,1] neg_lo:[1,0,0] neg_hi:[1,0,0]
	v_pk_fma_f32 v[20:21], v[220:221], v[108:109], v[202:203] op_sel_hi:[0,1,1] neg_lo:[1,0,0] neg_hi:[1,0,0]
	v_pk_fma_f32 v[12:13], v[220:221], v[108:109], v[210:211] op_sel:[1,0,0] op_sel_hi:[1,1,1] neg_lo:[1,0,0] neg_hi:[1,0,0]
	v_pk_mul_f32 v[222:223], v[22:23], v[118:119]
	v_pk_mul_f32 v[224:225], v[14:15], v[118:119]
	v_pk_fma_f32 v[222:223], v[24:25], v[120:121], v[222:223]
	v_pk_fma_f32 v[224:225], v[16:17], v[120:121], v[224:225]
	v_pk_fma_f32 v[222:223], v[18:19], v[122:123], v[222:223]
	v_pk_fma_f32 v[224:225], v[10:11], v[122:123], v[224:225]
	v_pk_fma_f32 v[222:223], v[20:21], v[124:125], v[222:223]
	v_pk_fma_f32 v[224:225], v[12:13], v[124:125], v[224:225]
	s_waitcnt lgkmcnt(0)
	ds_read_b128 v[86:89], v84 offset:2048
	ds_read_b128 v[90:93], v84 offset:2064
	ds_read_b128 v[94:97], v84 offset:6144
	ds_read_b128 v[98:101], v84 offset:6160
	ds_read_b128 v[102:105], v84 offset:10240
	ds_read_b128 v[106:109], v84 offset:10256
	ds_read_b128 v[118:121], v84 offset:18432
	ds_read_b128 v[122:125], v84 offset:18448
	v_pk_mul_f32 v[212:213], v[22:23], v[136:137]
	v_pk_mul_f32 v[216:217], v[14:15], v[136:137]
	v_pk_mul_f32 v[196:197], v[22:23], v[128:129]
	v_pk_mul_f32 v[204:205], v[14:15], v[128:129]
	v_pk_fma_f32 v[212:213], v[24:25], v[138:139], v[212:213]
	v_pk_fma_f32 v[216:217], v[16:17], v[138:139], v[216:217]
	v_pk_mul_f32 v[198:199], v[24:25], v[130:131]
	v_pk_mul_f32 v[206:207], v[16:17], v[130:131]
	v_pk_fma_f32 v[212:213], v[18:19], v[140:141], v[212:213]
	v_pk_fma_f32 v[216:217], v[10:11], v[140:141], v[216:217]
	v_pk_fma_f32 v[212:213], v[20:21], v[142:143], v[212:213]
	v_pk_fma_f32 v[216:217], v[12:13], v[142:143], v[216:217]
	v_add_f32_e32 v226, v222, v223
	v_add_f32_e32 v227, v224, v225
	v_add_f32_e32 v220, v212, v213
	v_add_f32_e32 v221, v216, v217
	v_pk_mul_f32 v[200:201], v[18:19], v[132:133]
	v_pk_mul_f32 v[208:209], v[10:11], v[132:133]
	ds_write_b64 v228, v[226:227] offset:3456
	v_add_f32_dpp v220, v220, v220 quad_perm:[1,0,3,2] row_mask:0xf bank_mask:0xf bound_ctrl:1
	v_add_f32_dpp v221, v221, v221 quad_perm:[1,0,3,2] row_mask:0xf bank_mask:0xf bound_ctrl:1
	v_pk_mul_f32 v[202:203], v[20:21], v[134:135]
	v_pk_mul_f32 v[210:211], v[12:13], v[134:135]
	v_add_f32_dpp v220, v220, v220 quad_perm:[2,3,0,1] row_mask:0xf bank_mask:0xf bound_ctrl:1
	v_add_f32_dpp v221, v221, v221 quad_perm:[2,3,0,1] row_mask:0xf bank_mask:0xf bound_ctrl:1
	s_nop 0
	v_add_f32_dpp v220, v220, v220 row_half_mirror row_mask:0xf bank_mask:0xf bound_ctrl:1
	v_add_f32_dpp v221, v221, v221 row_half_mirror row_mask:0xf bank_mask:0xf bound_ctrl:1
	s_nop 0
	v_pk_fma_f32 v[22:23], v[220:221], v[144:145], v[196:197] op_sel_hi:[0,1,1] neg_lo:[1,0,0] neg_hi:[1,0,0]
	v_pk_fma_f32 v[14:15], v[220:221], v[144:145], v[204:205] op_sel:[1,0,0] op_sel_hi:[1,1,1] neg_lo:[1,0,0] neg_hi:[1,0,0]
	v_pk_fma_f32 v[24:25], v[220:221], v[146:147], v[198:199] op_sel_hi:[0,1,1] neg_lo:[1,0,0] neg_hi:[1,0,0]
	v_pk_fma_f32 v[16:17], v[220:221], v[146:147], v[206:207] op_sel:[1,0,0] op_sel_hi:[1,1,1] neg_lo:[1,0,0] neg_hi:[1,0,0]
	v_pk_fma_f32 v[18:19], v[220:221], v[148:149], v[200:201] op_sel_hi:[0,1,1] neg_lo:[1,0,0] neg_hi:[1,0,0]
	v_pk_fma_f32 v[10:11], v[220:221], v[148:149], v[208:209] op_sel:[1,0,0] op_sel_hi:[1,1,1] neg_lo:[1,0,0] neg_hi:[1,0,0]
	v_pk_fma_f32 v[20:21], v[220:221], v[150:151], v[202:203] op_sel_hi:[0,1,1] neg_lo:[1,0,0] neg_hi:[1,0,0]
	v_pk_fma_f32 v[12:13], v[220:221], v[150:151], v[210:211] op_sel:[1,0,0] op_sel_hi:[1,1,1] neg_lo:[1,0,0] neg_hi:[1,0,0]
	v_pk_mul_f32 v[222:223], v[22:23], v[160:161]
	v_pk_mul_f32 v[224:225], v[14:15], v[160:161]
	v_pk_fma_f32 v[222:223], v[24:25], v[162:163], v[222:223]
	v_pk_fma_f32 v[224:225], v[16:17], v[162:163], v[224:225]
	v_pk_fma_f32 v[222:223], v[18:19], v[164:165], v[222:223]
	v_pk_fma_f32 v[224:225], v[10:11], v[164:165], v[224:225]
	v_pk_fma_f32 v[222:223], v[20:21], v[166:167], v[222:223]
	v_pk_fma_f32 v[224:225], v[12:13], v[166:167], v[224:225]
	s_waitcnt lgkmcnt(0)
; __device__ __forceinline__ void scan_rows(f32x2 (&X)[8], const ScanOps& o, const f32x4 (&b)[2], const f32x4 (&kd)[2], const f32x4 (&r)[2], const bool use_v, float& yA, float& yB) {
;     f32x2 aA = X[0] * o.kk[0].xy, aB = X[4] * o.kk[0].xy;
;     aA += X[1] * o.kk[0].zw; aB += X[5] * o.kk[0].zw;
;     aA += X[2] * o.kk[1].xy; aB += X[6] * o.kk[1].xy;
;     aA += X[3] * o.kk[1].zw; aB += X[7] * o.kk[1].zw;
;     const float saA = sum8(aA.x + aA.y), saB = sum8(aB.x + aB.y);
;     const f32x2 nA = (f32x2){-saA, -saA}, nB = (f32x2){-saB, -saB}, vA = (f32x2){o.v.x, o.v.x}, vB = (f32x2){o.v.y, o.v.y};
;     f32x2 tA, tB, accA, accB;
;     tA = X[0] * o.w[0].xy; tA += nA * b[0].xy; if (use_v) tA += vA * kd[0].xy; X[0] = tA; accA = tA * r[0].xy;
;     tB = X[4] * o.w[0].xy; tB += nB * b[0].xy; if (use_v) tB += vB * kd[0].xy; X[4] = tB; accB = tB * r[0].xy;
;     tA = X[1] * o.w[0].zw; tA += nA * b[0].zw; if (use_v) tA += vA * kd[0].zw; X[1] = tA; accA += tA * r[0].zw;
;     tB = X[5] * o.w[0].zw; tB += nB * b[0].zw; if (use_v) tB += vB * kd[0].zw; X[5] = tB; accB += tB * r[0].zw;
;     tA = X[2] * o.w[1].xy; tA += nA * b[1].xy; if (use_v) tA += vA * kd[1].xy; X[2] = tA; accA += tA * r[1].xy;
;     tB = X[6] * o.w[1].xy; tB += nB * b[1].xy; if (use_v) tB += vB * kd[1].xy; X[6] = tB; accB += tB * r[1].xy;
;     tA = X[3] * o.w[1].zw; tA += nA * b[1].zw; if (use_v) tA += vA * kd[1].zw; X[3] = tA; accA += tA * r[1].zw;
;     tB = X[7] * o.w[1].zw; tB += nB * b[1].zw; if (use_v) tB += vB * kd[1].zw; X[7] = tB; accB += tB * r[1].zw;
; __device__ void phase_scan(int c, const bf16_t* PROJ, const float* k_k, const bf16_t* Wd, const bf16_t* Bd, const float* k_a, bf16_t* Y, bf16_t* Q, float* FS, float* sm) {
;     ...
;                 for (int i = 0; i < 16; i += 2) {
;                     float yA = 0.f, yB = 0.f;
;                     scan_ld(ob, obv, i + 1, B);
;                     if (roleP) A.v = (f32x2){0.f, 0.f};
;                     scan_step1(X, A, ob + i * 64, yA, yB);
;                     *(f32x2*)(obw + i * 16 + 2 * vp) = (f32x2){yA, yB};
;                     if (i + 2 < 16) scan_ld(ob, obv, i + 2, A);
;                     if (roleP) B.v = (f32x2){0.f, 0.f};
;                     scan_step1(X, B, ob + (i + 1) * 64, yA, yB);
;                     *(f32x2*)(obw + (i + 1) * 16 + 2 * vp) = (f32x2){yA, yB};
;                 }
	ds_read_b128 v[128:131], v84 offset:2304
	ds_read_b128 v[132:135], v84 offset:2320
	ds_read_b128 v[136:139], v84 offset:6400
	ds_read_b128 v[140:143], v84 offset:6416
	ds_read_b128 v[144:147], v84 offset:10496
	ds_read_b128 v[148:151], v84 offset:10512
	ds_read_b128 v[160:163], v84 offset:18688
	ds_read_b128 v[164:167], v84 offset:18704
	v_pk_mul_f32 v[212:213], v[22:23], v[94:95]
	v_pk_mul_f32 v[216:217], v[14:15], v[94:95]
	v_pk_mul_f32 v[196:197], v[22:23], v[86:87]
	v_pk_mul_f32 v[204:205], v[14:15], v[86:87]
	v_pk_fma_f32 v[212:213], v[24:25], v[96:97], v[212:213]
	v_pk_fma_f32 v[216:217], v[16:17], v[96:97], v[216:217]
	v_pk_mul_f32 v[198:199], v[24:25], v[88:89]
	v_pk_mul_f32 v[206:207], v[16:17], v[88:89]
	v_pk_fma_f32 v[212:213], v[18:19], v[98:99], v[212:213]
	v_pk_fma_f32 v[216:217], v[10:11], v[98:99], v[216:217]
	v_pk_fma_f32 v[212:213], v[20:21], v[100:101], v[212:213]
	v_pk_fma_f32 v[216:217], v[12:13], v[100:101], v[216:217]
	v_add_f32_e32 v226, v222, v223
	v_add_f32_e32 v227, v224, v225
	v_add_f32_e32 v220, v212, v213
	v_add_f32_e32 v221, v216, v217
	v_pk_mul_f32 v[200:201], v[18:19], v[90:91]
	v_pk_mul_f32 v[208:209], v[10:11], v[90:91]
	ds_write_b64 v228, v[226:227] offset:4032
	v_add_f32_dpp v220, v220, v220 quad_perm:[1,0,3,2] row_mask:0xf bank_mask:0xf bound_ctrl:1
	v_add_f32_dpp v221, v221, v221 quad_perm:[1,0,3,2] row_mask:0xf bank_mask:0xf bound_ctrl:1
	v_pk_mul_f32 v[202:203], v[20:21], v[92:93]
	v_pk_mul_f32 v[210:211], v[12:13], v[92:93]
	v_add_f32_dpp v220, v220, v220 quad_perm:[2,3,0,1] row_mask:0xf bank_mask:0xf bound_ctrl:1
	v_add_f32_dpp v221, v221, v221 quad_perm:[2,3,0,1] row_mask:0xf bank_mask:0xf bound_ctrl:1
	s_nop 0
	v_add_f32_dpp v220, v220, v220 row_half_mirror row_mask:0xf bank_mask:0xf bound_ctrl:1
	v_add_f32_dpp v221, v221, v221 row_half_mirror row_mask:0xf bank_mask:0xf bound_ctrl:1
	s_nop 0
	v_pk_fma_f32 v[22:23], v[220:221], v[102:103], v[196:197] op_sel_hi:[0,1,1] neg_lo:[1,0,0] neg_hi:[1,0,0]
	v_pk_fma_f32 v[14:15], v[220:221], v[102:103], v[204:205] op_sel:[1,0,0] op_sel_hi:[1,1,1] neg_lo:[1,0,0] neg_hi:[1,0,0]
	v_pk_fma_f32 v[24:25], v[220:221], v[104:105], v[198:199] op_sel_hi:[0,1,1] neg_lo:[1,0,0] neg_hi:[1,0,0]
	v_pk_fma_f32 v[16:17], v[220:221], v[104:105], v[206:207] op_sel:[1,0,0] op_sel_hi:[1,1,1] neg_lo:[1,0,0] neg_hi:[1,0,0]
	v_pk_fma_f32 v[18:19], v[220:221], v[106:107], v[200:201] op_sel_hi:[0,1,1] neg_lo:[1,0,0] neg_hi:[1,0,0]
	v_pk_fma_f32 v[10:11], v[220:221], v[106:107], v[208:209] op_sel:[1,0,0] op_sel_hi:[1,1,1] neg_lo:[1,0,0] neg_hi:[1,0,0]
	v_pk_fma_f32 v[20:21], v[220:221], v[108:109], v[202:203] op_sel_hi:[0,1,1] neg_lo:[1,0,0] neg_hi:[1,0,0]
	v_pk_fma_f32 v[12:13], v[220:221], v[108:109], v[210:211] op_sel:[1,0,0] op_sel_hi:[1,1,1] neg_lo:[1,0,0] neg_hi:[1,0,0]
	v_pk_mul_f32 v[222:223], v[22:23], v[118:119]
	v_pk_mul_f32 v[224:225], v[14:15], v[118:119]
	v_pk_fma_f32 v[222:223], v[24:25], v[120:121], v[222:223]
	v_pk_fma_f32 v[224:225], v[16:17], v[120:121], v[224:225]
	v_pk_fma_f32 v[222:223], v[18:19], v[122:123], v[222:223]
	v_pk_fma_f32 v[224:225], v[10:11], v[122:123], v[224:225]
	v_pk_fma_f32 v[222:223], v[20:21], v[124:125], v[222:223]
	v_pk_fma_f32 v[224:225], v[12:13], v[124:125], v[224:225]
	s_waitcnt lgkmcnt(0)
	ds_read_b128 v[86:89], v84 offset:2560
	ds_read_b128 v[90:93], v84 offset:2576
	ds_read_b128 v[94:97], v84 offset:6656
	ds_read_b128 v[98:101], v84 offset:6672
	ds_read_b128 v[102:105], v84 offset:10752
	ds_read_b128 v[106:109], v84 offset:10768
	ds_read_b128 v[118:121], v84 offset:18944
	ds_read_b128 v[122:125], v84 offset:18960
	v_pk_mul_f32 v[212:213], v[22:23], v[136:137]
	v_pk_mul_f32 v[216:217], v[14:15], v[136:137]
	v_pk_mul_f32 v[196:197], v[22:23], v[128:129]
	v_pk_mul_f32 v[204:205], v[14:15], v[128:129]
	v_pk_fma_f32 v[212:213], v[24:25], v[138:139], v[212:213]
	v_pk_fma_f32 v[216:217], v[16:17], v[138:139], v[216:217]
	v_pk_mul_f32 v[198:199], v[24:25], v[130:131]
	v_pk_mul_f32 v[206:207], v[16:17], v[130:131]
	v_pk_fma_f32 v[212:213], v[18:19], v[140:141], v[212:213]
	v_pk_fma_f32 v[216:217], v[10:11], v[140:141], v[216:217]
	v_pk_fma_f32 v[212:213], v[20:21], v[142:143], v[212:213]
	v_pk_fma_f32 v[216:217], v[12:13], v[142:143], v[216:217]
	v_add_f32_e32 v226, v222, v223
	v_add_f32_e32 v227, v224, v225
	v_add_f32_e32 v220, v212, v213
	v_add_f32_e32 v221, v216, v217
	v_pk_mul_f32 v[200:201], v[18:19], v[132:133]
	v_pk_mul_f32 v[208:209], v[10:11], v[132:133]
	ds_write_b64 v228, v[226:227] offset:4608
	v_add_f32_dpp v220, v220, v220 quad_perm:[1,0,3,2] row_mask:0xf bank_mask:0xf bound_ctrl:1
	v_add_f32_dpp v221, v221, v221 quad_perm:[1,0,3,2] row_mask:0xf bank_mask:0xf bound_ctrl:1
	v_pk_mul_f32 v[202:203], v[20:21], v[134:135]
	v_pk_mul_f32 v[210:211], v[12:13], v[134:135]
	v_add_f32_dpp v220, v220, v220 quad_perm:[2,3,0,1] row_mask:0xf bank_mask:0xf bound_ctrl:1
	v_add_f32_dpp v221, v221, v221 quad_perm:[2,3,0,1] row_mask:0xf bank_mask:0xf bound_ctrl:1
	s_nop 0
	v_add_f32_dpp v220, v220, v220 row_half_mirror row_mask:0xf bank_mask:0xf bound_ctrl:1
	v_add_f32_dpp v221, v221, v221 row_half_mirror row_mask:0xf bank_mask:0xf bound_ctrl:1
	s_nop 0
	v_pk_fma_f32 v[22:23], v[220:221], v[144:145], v[196:197] op_sel_hi:[0,1,1] neg_lo:[1,0,0] neg_hi:[1,0,0]
	v_pk_fma_f32 v[14:15], v[220:221], v[144:145], v[204:205] op_sel:[1,0,0] op_sel_hi:[1,1,1] neg_lo:[1,0,0] neg_hi:[1,0,0]
	v_pk_fma_f32 v[24:25], v[220:221], v[146:147], v[198:199] op_sel_hi:[0,1,1] neg_lo:[1,0,0] neg_hi:[1,0,0]
	v_pk_fma_f32 v[16:17], v[220:221], v[146:147], v[206:207] op_sel:[1,0,0] op_sel_hi:[1,1,1] neg_lo:[1,0,0] neg_hi:[1,0,0]
	v_pk_fma_f32 v[18:19], v[220:221], v[148:149], v[200:201] op_sel_hi:[0,1,1] neg_lo:[1,0,0] neg_hi:[1,0,0]
	v_pk_fma_f32 v[10:11], v[220:221], v[148:149], v[208:209] op_sel:[1,0,0] op_sel_hi:[1,1,1] neg_lo:[1,0,0] neg_hi:[1,0,0]
	v_pk_fma_f32 v[20:21], v[220:221], v[150:151], v[202:203] op_sel_hi:[0,1,1] neg_lo:[1,0,0] neg_hi:[1,0,0]
	v_pk_fma_f32 v[12:13], v[220:221], v[150:151], v[210:211] op_sel:[1,0,0] op_sel_hi:[1,1,1] neg_lo:[1,0,0] neg_hi:[1,0,0]
	v_pk_mul_f32 v[222:223], v[22:23], v[160:161]
	v_pk_mul_f32 v[224:225], v[14:15], v[160:161]
	v_pk_fma_f32 v[222:223], v[24:25], v[162:163], v[222:223]
	v_pk_fma_f32 v[224:225], v[16:17], v[162:163], v[224:225]
	v_pk_fma_f32 v[222:223], v[18:19], v[164:165], v[222:223]
	v_pk_fma_f32 v[224:225], v[10:11], v[164:165], v[224:225]
	v_pk_fma_f32 v[222:223], v[20:21], v[166:167], v[222:223]
	v_pk_fma_f32 v[224:225], v[12:13], v[166:167], v[224:225]
	s_waitcnt lgkmcnt(0)
; __device__ __forceinline__ void scan_rows(f32x2 (&X)[8], const ScanOps& o, const f32x4 (&b)[2], const f32x4 (&kd)[2], const f32x4 (&r)[2], const bool use_v, float& yA, float& yB) {
;     f32x2 aA = X[0] * o.kk[0].xy, aB = X[4] * o.kk[0].xy;
;     aA += X[1] * o.kk[0].zw; aB += X[5] * o.kk[0].zw;
;     aA += X[2] * o.kk[1].xy; aB += X[6] * o.kk[1].xy;
;     aA += X[3] * o.kk[1].zw; aB += X[7] * o.kk[1].zw;
;     const float saA = sum8(aA.x + aA.y), saB = sum8(aB.x + aB.y);
;     const f32x2 nA = (f32x2){-saA, -saA}, nB = (f32x2){-saB, -saB}, vA = (f32x2){o.v.x, o.v.x}, vB = (f32x2){o.v.y, o.v.y};
;     f32x2 tA, tB, accA, accB;
;     tA = X[0] * o.w[0].xy; tA += nA * b[0].xy; if (use_v) tA += vA * kd[0].xy; X[0] = tA; accA = tA * r[0].xy;
;     tB = X[4] * o.w[0].xy; tB += nB * b[0].xy; if (use_v) tB += vB * kd[0].xy; X[4] = tB; accB = tB * r[0].xy;
;     tA = X[1] * o.w[0].zw; tA += nA * b[0].zw; if (use_v) tA += vA * kd[0].zw; X[1] = tA; accA += tA * r[0].zw;
;     tB = X[5] * o.w[0].zw; tB += nB * b[0].zw; if (use_v) tB += vB * kd[0].zw; X[5] = tB; accB += tB * r[0].zw;
;     tA = X[2] * o.w[1].xy; tA += nA * b[1].xy; if (use_v) tA += vA * kd[1].xy; X[2] = tA; accA += tA * r[1].xy;
;     tB = X[6] * o.w[1].xy; tB += nB * b[1].xy; if (use_v) tB += vB * kd[1].xy; X[6] = tB; accB += tB * r[1].xy;
;     tA = X[3] * o.w[1].zw; tA += nA * b[1].zw; if (use_v) tA += vA * kd[1].zw; X[3] = tA; accA += tA * r[1].zw;
;     tB = X[7] * o.w[1].zw; tB += nB * b[1].zw; if (use_v) tB += vB * kd[1].zw; X[7] = tB; accB += tB * r[1].zw;
; __device__ void phase_scan(int c, const bf16_t* PROJ, const float* k_k, const bf16_t* Wd, const bf16_t* Bd, const float* k_a, bf16_t* Y, bf16_t* Q, float* FS, float* sm) {
;     ...
;                 for (int i = 0; i < 16; i += 2) {
;                     float yA = 0.f, yB = 0.f;
;                     scan_ld(ob, obv, i + 1, B);
;                     if (roleP) A.v = (f32x2){0.f, 0.f};
;                     scan_step1(X, A, ob + i * 64, yA, yB);
;                     *(f32x2*)(obw + i * 16 + 2 * vp) = (f32x2){yA, yB};
;                     if (i + 2 < 16) scan_ld(ob, obv, i + 2, A);
;                     if (roleP) B.v = (f32x2){0.f, 0.f};
;                     scan_step1(X, B, ob + (i + 1) * 64, yA, yB);
;                     *(f32x2*)(obw + (i + 1) * 16 + 2 * vp) = (f32x2){yA, yB};
;                 }
	ds_read_b128 v[128:131], v84 offset:2816
	ds_read_b128 v[132:135], v84 offset:2832
	ds_read_b128 v[136:139], v84 offset:6912
	ds_read_b128 v[140:143], v84 offset:6928
	ds_read_b128 v[144:147], v84 offset:11008
	ds_read_b128 v[148:151], v84 offset:11024
	ds_read_b128 v[160:163], v84 offset:19200
	ds_read_b128 v[164:167], v84 offset:19216
	v_pk_mul_f32 v[212:213], v[22:23], v[94:95]
	v_pk_mul_f32 v[216:217], v[14:15], v[94:95]
	v_pk_mul_f32 v[196:197], v[22:23], v[86:87]
	v_pk_mul_f32 v[204:205], v[14:15], v[86:87]
	v_pk_fma_f32 v[212:213], v[24:25], v[96:97], v[212:213]
	v_pk_fma_f32 v[216:217], v[16:17], v[96:97], v[216:217]
	v_pk_mul_f32 v[198:199], v[24:25], v[88:89]
	v_pk_mul_f32 v[206:207], v[16:17], v[88:89]
	v_pk_fma_f32 v[212:213], v[18:19], v[98:99], v[212:213]
	v_pk_fma_f32 v[216:217], v[10:11], v[98:99], v[216:217]
	v_pk_fma_f32 v[212:213], v[20:21], v[100:101], v[212:213]
	v_pk_fma_f32 v[216:217], v[12:13], v[100:101], v[216:217]
	v_add_f32_e32 v226, v222, v223
	v_add_f32_e32 v227, v224, v225
	v_add_f32_e32 v220, v212, v213
	v_add_f32_e32 v221, v216, v217
	v_pk_mul_f32 v[200:201], v[18:19], v[90:91]
	v_pk_mul_f32 v[208:209], v[10:11], v[90:91]
	ds_write_b64 v228, v[226:227] offset:5184
	v_add_f32_dpp v220, v220, v220 quad_perm:[1,0,3,2] row_mask:0xf bank_mask:0xf bound_ctrl:1
	v_add_f32_dpp v221, v221, v221 quad_perm:[1,0,3,2] row_mask:0xf bank_mask:0xf bound_ctrl:1
	v_pk_mul_f32 v[202:203], v[20:21], v[92:93]
	v_pk_mul_f32 v[210:211], v[12:13], v[92:93]
	v_add_f32_dpp v220, v220, v220 quad_perm:[2,3,0,1] row_mask:0xf bank_mask:0xf bound_ctrl:1
	v_add_f32_dpp v221, v221, v221 quad_perm:[2,3,0,1] row_mask:0xf bank_mask:0xf bound_ctrl:1
	s_nop 0
	v_add_f32_dpp v220, v220, v220 row_half_mirror row_mask:0xf bank_mask:0xf bound_ctrl:1
	v_add_f32_dpp v221, v221, v221 row_half_mirror row_mask:0xf bank_mask:0xf bound_ctrl:1
	s_nop 0
	v_pk_fma_f32 v[22:23], v[220:221], v[102:103], v[196:197] op_sel_hi:[0,1,1] neg_lo:[1,0,0] neg_hi:[1,0,0]
	v_pk_fma_f32 v[14:15], v[220:221], v[102:103], v[204:205] op_sel:[1,0,0] op_sel_hi:[1,1,1] neg_lo:[1,0,0] neg_hi:[1,0,0]
	v_pk_fma_f32 v[24:25], v[220:221], v[104:105], v[198:199] op_sel_hi:[0,1,1] neg_lo:[1,0,0] neg_hi:[1,0,0]
	v_pk_fma_f32 v[16:17], v[220:221], v[104:105], v[206:207] op_sel:[1,0,0] op_sel_hi:[1,1,1] neg_lo:[1,0,0] neg_hi:[1,0,0]
	v_pk_fma_f32 v[18:19], v[220:221], v[106:107], v[200:201] op_sel_hi:[0,1,1] neg_lo:[1,0,0] neg_hi:[1,0,0]
	v_pk_fma_f32 v[10:11], v[220:221], v[106:107], v[208:209] op_sel:[1,0,0] op_sel_hi:[1,1,1] neg_lo:[1,0,0] neg_hi:[1,0,0]
	v_pk_fma_f32 v[20:21], v[220:221], v[108:109], v[202:203] op_sel_hi:[0,1,1] neg_lo:[1,0,0] neg_hi:[1,0,0]
	v_pk_fma_f32 v[12:13], v[220:221], v[108:109], v[210:211] op_sel:[1,0,0] op_sel_hi:[1,1,1] neg_lo:[1,0,0] neg_hi:[1,0,0]
	v_pk_mul_f32 v[222:223], v[22:23], v[118:119]
	v_pk_mul_f32 v[224:225], v[14:15], v[118:119]
	v_pk_fma_f32 v[222:223], v[24:25], v[120:121], v[222:223]
	v_pk_fma_f32 v[224:225], v[16:17], v[120:121], v[224:225]
	v_pk_fma_f32 v[222:223], v[18:19], v[122:123], v[222:223]
	v_pk_fma_f32 v[224:225], v[10:11], v[122:123], v[224:225]
	v_pk_fma_f32 v[222:223], v[20:21], v[124:125], v[222:223]
	v_pk_fma_f32 v[224:225], v[12:13], v[124:125], v[224:225]
	s_waitcnt lgkmcnt(0)
	ds_read_b128 v[86:89], v84 offset:3072
	ds_read_b128 v[90:93], v84 offset:3088
	ds_read_b128 v[94:97], v84 offset:7168
	ds_read_b128 v[98:101], v84 offset:7184
	ds_read_b128 v[102:105], v84 offset:11264
	ds_read_b128 v[106:109], v84 offset:11280
	ds_read_b128 v[118:121], v84 offset:19456
	ds_read_b128 v[122:125], v84 offset:19472
	v_pk_mul_f32 v[212:213], v[22:23], v[136:137]
	v_pk_mul_f32 v[216:217], v[14:15], v[136:137]
	v_pk_mul_f32 v[196:197], v[22:23], v[128:129]
	v_pk_mul_f32 v[204:205], v[14:15], v[128:129]
	v_pk_fma_f32 v[212:213], v[24:25], v[138:139], v[212:213]
	v_pk_fma_f32 v[216:217], v[16:17], v[138:139], v[216:217]
	v_pk_mul_f32 v[198:199], v[24:25], v[130:131]
	v_pk_mul_f32 v[206:207], v[16:17], v[130:131]
	v_pk_fma_f32 v[212:213], v[18:19], v[140:141], v[212:213]
	v_pk_fma_f32 v[216:217], v[10:11], v[140:141], v[216:217]
	v_pk_fma_f32 v[212:213], v[20:21], v[142:143], v[212:213]
	v_pk_fma_f32 v[216:217], v[12:13], v[142:143], v[216:217]
	v_add_f32_e32 v226, v222, v223
	v_add_f32_e32 v227, v224, v225
	v_add_f32_e32 v220, v212, v213
	v_add_f32_e32 v221, v216, v217
	v_pk_mul_f32 v[200:201], v[18:19], v[132:133]
	v_pk_mul_f32 v[208:209], v[10:11], v[132:133]
	ds_write_b64 v228, v[226:227] offset:5760
	v_add_f32_dpp v220, v220, v220 quad_perm:[1,0,3,2] row_mask:0xf bank_mask:0xf bound_ctrl:1
	v_add_f32_dpp v221, v221, v221 quad_perm:[1,0,3,2] row_mask:0xf bank_mask:0xf bound_ctrl:1
	v_pk_mul_f32 v[202:203], v[20:21], v[134:135]
	v_pk_mul_f32 v[210:211], v[12:13], v[134:135]
	v_add_f32_dpp v220, v220, v220 quad_perm:[2,3,0,1] row_mask:0xf bank_mask:0xf bound_ctrl:1
	v_add_f32_dpp v221, v221, v221 quad_perm:[2,3,0,1] row_mask:0xf bank_mask:0xf bound_ctrl:1
	s_nop 0
	v_add_f32_dpp v220, v220, v220 row_half_mirror row_mask:0xf bank_mask:0xf bound_ctrl:1
	v_add_f32_dpp v221, v221, v221 row_half_mirror row_mask:0xf bank_mask:0xf bound_ctrl:1
	s_nop 0
	v_pk_fma_f32 v[22:23], v[220:221], v[144:145], v[196:197] op_sel_hi:[0,1,1] neg_lo:[1,0,0] neg_hi:[1,0,0]
	v_pk_fma_f32 v[14:15], v[220:221], v[144:145], v[204:205] op_sel:[1,0,0] op_sel_hi:[1,1,1] neg_lo:[1,0,0] neg_hi:[1,0,0]
	v_pk_fma_f32 v[24:25], v[220:221], v[146:147], v[198:199] op_sel_hi:[0,1,1] neg_lo:[1,0,0] neg_hi:[1,0,0]
	v_pk_fma_f32 v[16:17], v[220:221], v[146:147], v[206:207] op_sel:[1,0,0] op_sel_hi:[1,1,1] neg_lo:[1,0,0] neg_hi:[1,0,0]
	v_pk_fma_f32 v[18:19], v[220:221], v[148:149], v[200:201] op_sel_hi:[0,1,1] neg_lo:[1,0,0] neg_hi:[1,0,0]
	v_pk_fma_f32 v[10:11], v[220:221], v[148:149], v[208:209] op_sel:[1,0,0] op_sel_hi:[1,1,1] neg_lo:[1,0,0] neg_hi:[1,0,0]
	v_pk_fma_f32 v[20:21], v[220:221], v[150:151], v[202:203] op_sel_hi:[0,1,1] neg_lo:[1,0,0] neg_hi:[1,0,0]
	v_pk_fma_f32 v[12:13], v[220:221], v[150:151], v[210:211] op_sel:[1,0,0] op_sel_hi:[1,1,1] neg_lo:[1,0,0] neg_hi:[1,0,0]
	v_pk_mul_f32 v[222:223], v[22:23], v[160:161]
	v_pk_mul_f32 v[224:225], v[14:15], v[160:161]
	v_pk_fma_f32 v[222:223], v[24:25], v[162:163], v[222:223]
	v_pk_fma_f32 v[224:225], v[16:17], v[162:163], v[224:225]
	v_pk_fma_f32 v[222:223], v[18:19], v[164:165], v[222:223]
	v_pk_fma_f32 v[224:225], v[10:11], v[164:165], v[224:225]
	v_pk_fma_f32 v[222:223], v[20:21], v[166:167], v[222:223]
	v_pk_fma_f32 v[224:225], v[12:13], v[166:167], v[224:225]
	s_waitcnt lgkmcnt(0)
; __device__ __forceinline__ void scan_rows(f32x2 (&X)[8], const ScanOps& o, const f32x4 (&b)[2], const f32x4 (&kd)[2], const f32x4 (&r)[2], const bool use_v, float& yA, float& yB) {
;     f32x2 aA = X[0] * o.kk[0].xy, aB = X[4] * o.kk[0].xy;
;     aA += X[1] * o.kk[0].zw; aB += X[5] * o.kk[0].zw;
;     aA += X[2] * o.kk[1].xy; aB += X[6] * o.kk[1].xy;
;     aA += X[3] * o.kk[1].zw; aB += X[7] * o.kk[1].zw;
;     const float saA = sum8(aA.x + aA.y), saB = sum8(aB.x + aB.y);
;     const f32x2 nA = (f32x2){-saA, -saA}, nB = (f32x2){-saB, -saB}, vA = (f32x2){o.v.x, o.v.x}, vB = (f32x2){o.v.y, o.v.y};
;     f32x2 tA, tB, accA, accB;
;     tA = X[0] * o.w[0].xy; tA += nA * b[0].xy; if (use_v) tA += vA * kd[0].xy; X[0] = tA; accA = tA * r[0].xy;
;     tB = X[4] * o.w[0].xy; tB += nB * b[0].xy; if (use_v) tB += vB * kd[0].xy; X[4] = tB; accB = tB * r[0].xy;
;     tA = X[1] * o.w[0].zw; tA += nA * b[0].zw; if (use_v) tA += vA * kd[0].zw; X[1] = tA; accA += tA * r[0].zw;
;     tB = X[5] * o.w[0].zw; tB += nB * b[0].zw; if (use_v) tB += vB * kd[0].zw; X[5] = tB; accB += tB * r[0].zw;
;     tA = X[2] * o.w[1].xy; tA += nA * b[1].xy; if (use_v) tA += vA * kd[1].xy; X[2] = tA; accA += tA * r[1].xy;
;     tB = X[6] * o.w[1].xy; tB += nB * b[1].xy; if (use_v) tB += vB * kd[1].xy; X[6] = tB; accB += tB * r[1].xy;
;     tA = X[3] * o.w[1].zw; tA += nA * b[1].zw; if (use_v) tA += vA * kd[1].zw; X[3] = tA; accA += tA * r[1].zw;
;     tB = X[7] * o.w[1].zw; tB += nB * b[1].zw; if (use_v) tB += vB * kd[1].zw; X[7] = tB; accB += tB * r[1].zw;
; __device__ void phase_scan(int c, const bf16_t* PROJ, const float* k_k, const bf16_t* Wd, const bf16_t* Bd, const float* k_a, bf16_t* Y, bf16_t* Q, float* FS, float* sm) {
;     ...
;                 for (int i = 0; i < 16; i += 2) {
;                     float yA = 0.f, yB = 0.f;
;                     scan_ld(ob, obv, i + 1, B);
;                     if (roleP) A.v = (f32x2){0.f, 0.f};
;                     scan_step1(X, A, ob + i * 64, yA, yB);
;                     *(f32x2*)(obw + i * 16 + 2 * vp) = (f32x2){yA, yB};
;                     if (i + 2 < 16) scan_ld(ob, obv, i + 2, A);
;                     if (roleP) B.v = (f32x2){0.f, 0.f};
;                     scan_step1(X, B, ob + (i + 1) * 64, yA, yB);
;                     *(f32x2*)(obw + (i + 1) * 16 + 2 * vp) = (f32x2){yA, yB};
;                 }
	ds_read_b128 v[128:131], v84 offset:3328
	ds_read_b128 v[132:135], v84 offset:3344
	ds_read_b128 v[136:139], v84 offset:7424
	ds_read_b128 v[140:143], v84 offset:7440
	ds_read_b128 v[144:147], v84 offset:11520
	ds_read_b128 v[148:151], v84 offset:11536
	ds_read_b128 v[160:163], v84 offset:19712
	ds_read_b128 v[164:167], v84 offset:19728
	v_pk_mul_f32 v[212:213], v[22:23], v[94:95]
	v_pk_mul_f32 v[216:217], v[14:15], v[94:95]
	v_pk_mul_f32 v[196:197], v[22:23], v[86:87]
	v_pk_mul_f32 v[204:205], v[14:15], v[86:87]
	v_pk_fma_f32 v[212:213], v[24:25], v[96:97], v[212:213]
	v_pk_fma_f32 v[216:217], v[16:17], v[96:97], v[216:217]
	v_pk_mul_f32 v[198:199], v[24:25], v[88:89]
	v_pk_mul_f32 v[206:207], v[16:17], v[88:89]
	v_pk_fma_f32 v[212:213], v[18:19], v[98:99], v[212:213]
	v_pk_fma_f32 v[216:217], v[10:11], v[98:99], v[216:217]
	v_pk_fma_f32 v[212:213], v[20:21], v[100:101], v[212:213]
	v_pk_fma_f32 v[216:217], v[12:13], v[100:101], v[216:217]
	v_add_f32_e32 v226, v222, v223
	v_add_f32_e32 v227, v224, v225
	v_add_f32_e32 v220, v212, v213
	v_add_f32_e32 v221, v216, v217
	v_pk_mul_f32 v[200:201], v[18:19], v[90:91]
	v_pk_mul_f32 v[208:209], v[10:11], v[90:91]
	ds_write_b64 v228, v[226:227] offset:6336
	v_add_f32_dpp v220, v220, v220 quad_perm:[1,0,3,2] row_mask:0xf bank_mask:0xf bound_ctrl:1
	v_add_f32_dpp v221, v221, v221 quad_perm:[1,0,3,2] row_mask:0xf bank_mask:0xf bound_ctrl:1
	v_pk_mul_f32 v[202:203], v[20:21], v[92:93]
	v_pk_mul_f32 v[210:211], v[12:13], v[92:93]
	v_add_f32_dpp v220, v220, v220 quad_perm:[2,3,0,1] row_mask:0xf bank_mask:0xf bound_ctrl:1
	v_add_f32_dpp v221, v221, v221 quad_perm:[2,3,0,1] row_mask:0xf bank_mask:0xf bound_ctrl:1
	s_nop 0
	v_add_f32_dpp v220, v220, v220 row_half_mirror row_mask:0xf bank_mask:0xf bound_ctrl:1
	v_add_f32_dpp v221, v221, v221 row_half_mirror row_mask:0xf bank_mask:0xf bound_ctrl:1
	s_nop 0
	v_pk_fma_f32 v[22:23], v[220:221], v[102:103], v[196:197] op_sel_hi:[0,1,1] neg_lo:[1,0,0] neg_hi:[1,0,0]
	v_pk_fma_f32 v[14:15], v[220:221], v[102:103], v[204:205] op_sel:[1,0,0] op_sel_hi:[1,1,1] neg_lo:[1,0,0] neg_hi:[1,0,0]
	v_pk_fma_f32 v[24:25], v[220:221], v[104:105], v[198:199] op_sel_hi:[0,1,1] neg_lo:[1,0,0] neg_hi:[1,0,0]
	v_pk_fma_f32 v[16:17], v[220:221], v[104:105], v[206:207] op_sel:[1,0,0] op_sel_hi:[1,1,1] neg_lo:[1,0,0] neg_hi:[1,0,0]
	v_pk_fma_f32 v[18:19], v[220:221], v[106:107], v[200:201] op_sel_hi:[0,1,1] neg_lo:[1,0,0] neg_hi:[1,0,0]
	v_pk_fma_f32 v[10:11], v[220:221], v[106:107], v[208:209] op_sel:[1,0,0] op_sel_hi:[1,1,1] neg_lo:[1,0,0] neg_hi:[1,0,0]
	v_pk_fma_f32 v[20:21], v[220:221], v[108:109], v[202:203] op_sel_hi:[0,1,1] neg_lo:[1,0,0] neg_hi:[1,0,0]
	v_pk_fma_f32 v[12:13], v[220:221], v[108:109], v[210:211] op_sel:[1,0,0] op_sel_hi:[1,1,1] neg_lo:[1,0,0] neg_hi:[1,0,0]
	v_pk_mul_f32 v[222:223], v[22:23], v[118:119]
	v_pk_mul_f32 v[224:225], v[14:15], v[118:119]
	v_pk_fma_f32 v[222:223], v[24:25], v[120:121], v[222:223]
	v_pk_fma_f32 v[224:225], v[16:17], v[120:121], v[224:225]
	v_pk_fma_f32 v[222:223], v[18:19], v[122:123], v[222:223]
	v_pk_fma_f32 v[224:225], v[10:11], v[122:123], v[224:225]
	v_pk_fma_f32 v[222:223], v[20:21], v[124:125], v[222:223]
	v_pk_fma_f32 v[224:225], v[12:13], v[124:125], v[224:225]
	s_waitcnt lgkmcnt(0)
	ds_read_b128 v[86:89], v84 offset:3584
	ds_read_b128 v[90:93], v84 offset:3600
	ds_read_b128 v[94:97], v84 offset:7680
	ds_read_b128 v[98:101], v84 offset:7696
	ds_read_b128 v[102:105], v84 offset:11776
	ds_read_b128 v[106:109], v84 offset:11792
	ds_read_b128 v[118:121], v84 offset:19968
	ds_read_b128 v[122:125], v84 offset:19984
	v_pk_mul_f32 v[212:213], v[22:23], v[136:137]
	v_pk_mul_f32 v[216:217], v[14:15], v[136:137]
	v_pk_mul_f32 v[196:197], v[22:23], v[128:129]
	v_pk_mul_f32 v[204:205], v[14:15], v[128:129]
	v_pk_fma_f32 v[212:213], v[24:25], v[138:139], v[212:213]
	v_pk_fma_f32 v[216:217], v[16:17], v[138:139], v[216:217]
	v_pk_mul_f32 v[198:199], v[24:25], v[130:131]
	v_pk_mul_f32 v[206:207], v[16:17], v[130:131]
	v_pk_fma_f32 v[212:213], v[18:19], v[140:141], v[212:213]
	v_pk_fma_f32 v[216:217], v[10:11], v[140:141], v[216:217]
	v_pk_fma_f32 v[212:213], v[20:21], v[142:143], v[212:213]
	v_pk_fma_f32 v[216:217], v[12:13], v[142:143], v[216:217]
	v_add_f32_e32 v226, v222, v223
	v_add_f32_e32 v227, v224, v225
	v_add_f32_e32 v220, v212, v213
	v_add_f32_e32 v221, v216, v217
	v_pk_mul_f32 v[200:201], v[18:19], v[132:133]
	v_pk_mul_f32 v[208:209], v[10:11], v[132:133]
	ds_write_b64 v228, v[226:227] offset:6912
	v_add_f32_dpp v220, v220, v220 quad_perm:[1,0,3,2] row_mask:0xf bank_mask:0xf bound_ctrl:1
	v_add_f32_dpp v221, v221, v221 quad_perm:[1,0,3,2] row_mask:0xf bank_mask:0xf bound_ctrl:1
	v_pk_mul_f32 v[202:203], v[20:21], v[134:135]
	v_pk_mul_f32 v[210:211], v[12:13], v[134:135]
	v_add_f32_dpp v220, v220, v220 quad_perm:[2,3,0,1] row_mask:0xf bank_mask:0xf bound_ctrl:1
	v_add_f32_dpp v221, v221, v221 quad_perm:[2,3,0,1] row_mask:0xf bank_mask:0xf bound_ctrl:1
	s_nop 0
	v_add_f32_dpp v220, v220, v220 row_half_mirror row_mask:0xf bank_mask:0xf bound_ctrl:1
	v_add_f32_dpp v221, v221, v221 row_half_mirror row_mask:0xf bank_mask:0xf bound_ctrl:1
	s_nop 0
	v_pk_fma_f32 v[22:23], v[220:221], v[144:145], v[196:197] op_sel_hi:[0,1,1] neg_lo:[1,0,0] neg_hi:[1,0,0]
	v_pk_fma_f32 v[14:15], v[220:221], v[144:145], v[204:205] op_sel:[1,0,0] op_sel_hi:[1,1,1] neg_lo:[1,0,0] neg_hi:[1,0,0]
	v_pk_fma_f32 v[24:25], v[220:221], v[146:147], v[198:199] op_sel_hi:[0,1,1] neg_lo:[1,0,0] neg_hi:[1,0,0]
	v_pk_fma_f32 v[16:17], v[220:221], v[146:147], v[206:207] op_sel:[1,0,0] op_sel_hi:[1,1,1] neg_lo:[1,0,0] neg_hi:[1,0,0]
	v_pk_fma_f32 v[18:19], v[220:221], v[148:149], v[200:201] op_sel_hi:[0,1,1] neg_lo:[1,0,0] neg_hi:[1,0,0]
	v_pk_fma_f32 v[10:11], v[220:221], v[148:149], v[208:209] op_sel:[1,0,0] op_sel_hi:[1,1,1] neg_lo:[1,0,0] neg_hi:[1,0,0]
	v_pk_fma_f32 v[20:21], v[220:221], v[150:151], v[202:203] op_sel_hi:[0,1,1] neg_lo:[1,0,0] neg_hi:[1,0,0]
	v_pk_fma_f32 v[12:13], v[220:221], v[150:151], v[210:211] op_sel:[1,0,0] op_sel_hi:[1,1,1] neg_lo:[1,0,0] neg_hi:[1,0,0]
	v_pk_mul_f32 v[222:223], v[22:23], v[160:161]
	v_pk_mul_f32 v[224:225], v[14:15], v[160:161]
	v_pk_fma_f32 v[222:223], v[24:25], v[162:163], v[222:223]
	v_pk_fma_f32 v[224:225], v[16:17], v[162:163], v[224:225]
	v_pk_fma_f32 v[222:223], v[18:19], v[164:165], v[222:223]
	v_pk_fma_f32 v[224:225], v[10:11], v[164:165], v[224:225]
	v_pk_fma_f32 v[222:223], v[20:21], v[166:167], v[222:223]
	v_pk_fma_f32 v[224:225], v[12:13], v[166:167], v[224:225]
	s_waitcnt lgkmcnt(0)
; __device__ __forceinline__ void scan_rows(f32x2 (&X)[8], const ScanOps& o, const f32x4 (&b)[2], const f32x4 (&kd)[2], const f32x4 (&r)[2], const bool use_v, float& yA, float& yB) {
;     f32x2 aA = X[0] * o.kk[0].xy, aB = X[4] * o.kk[0].xy;
;     aA += X[1] * o.kk[0].zw; aB += X[5] * o.kk[0].zw;
;     aA += X[2] * o.kk[1].xy; aB += X[6] * o.kk[1].xy;
;     aA += X[3] * o.kk[1].zw; aB += X[7] * o.kk[1].zw;
;     const float saA = sum8(aA.x + aA.y), saB = sum8(aB.x + aB.y);
;     const f32x2 nA = (f32x2){-saA, -saA}, nB = (f32x2){-saB, -saB}, vA = (f32x2){o.v.x, o.v.x}, vB = (f32x2){o.v.y, o.v.y};
;     f32x2 tA, tB, accA, accB;
;     tA = X[0] * o.w[0].xy; tA += nA * b[0].xy; if (use_v) tA += vA * kd[0].xy; X[0] = tA; accA = tA * r[0].xy;
;     tB = X[4] * o.w[0].xy; tB += nB * b[0].xy; if (use_v) tB += vB * kd[0].xy; X[4] = tB; accB = tB * r[0].xy;
;     tA = X[1] * o.w[0].zw; tA += nA * b[0].zw; if (use_v) tA += vA * kd[0].zw; X[1] = tA; accA += tA * r[0].zw;
;     tB = X[5] * o.w[0].zw; tB += nB * b[0].zw; if (use_v) tB += vB * kd[0].zw; X[5] = tB; accB += tB * r[0].zw;
;     tA = X[2] * o.w[1].xy; tA += nA * b[1].xy; if (use_v) tA += vA * kd[1].xy; X[2] = tA; accA += tA * r[1].xy;
;     tB = X[6] * o.w[1].xy; tB += nB * b[1].xy; if (use_v) tB += vB * kd[1].xy; X[6] = tB; accB += tB * r[1].xy;
;     tA = X[3] * o.w[1].zw; tA += nA * b[1].zw; if (use_v) tA += vA * kd[1].zw; X[3] = tA; accA += tA * r[1].zw;
;     tB = X[7] * o.w[1].zw; tB += nB * b[1].zw; if (use_v) tB += vB * kd[1].zw; X[7] = tB; accB += tB * r[1].zw;
; __device__ void phase_scan(int c, const bf16_t* PROJ, const float* k_k, const bf16_t* Wd, const bf16_t* Bd, const float* k_a, bf16_t* Y, bf16_t* Q, float* FS, float* sm) {
;     ...
;                 for (int i = 0; i < 16; i += 2) {
;                     float yA = 0.f, yB = 0.f;
;                     scan_ld(ob, obv, i + 1, B);
;                     if (roleP) A.v = (f32x2){0.f, 0.f};
;                     scan_step1(X, A, ob + i * 64, yA, yB);
;                     *(f32x2*)(obw + i * 16 + 2 * vp) = (f32x2){yA, yB};
;                     if (i + 2 < 16) scan_ld(ob, obv, i + 2, A);
;                     if (roleP) B.v = (f32x2){0.f, 0.f};
;                     scan_step1(X, B, ob + (i + 1) * 64, yA, yB);
;                     *(f32x2*)(obw + (i + 1) * 16 + 2 * vp) = (f32x2){yA, yB};
;                 }
	ds_read_b128 v[128:131], v84 offset:3840
	ds_read_b128 v[132:135], v84 offset:3856
	ds_read_b128 v[136:139], v84 offset:7936
	ds_read_b128 v[140:143], v84 offset:7952
	ds_read_b128 v[144:147], v84 offset:12032
	ds_read_b128 v[148:151], v84 offset:12048
	ds_read_b128 v[160:163], v84 offset:20224
	ds_read_b128 v[164:167], v84 offset:20240
	v_pk_mul_f32 v[212:213], v[22:23], v[94:95]
	v_pk_mul_f32 v[216:217], v[14:15], v[94:95]
	v_pk_mul_f32 v[196:197], v[22:23], v[86:87]
	v_pk_mul_f32 v[204:205], v[14:15], v[86:87]
	v_pk_fma_f32 v[212:213], v[24:25], v[96:97], v[212:213]
	v_pk_fma_f32 v[216:217], v[16:17], v[96:97], v[216:217]
	v_pk_mul_f32 v[198:199], v[24:25], v[88:89]
	v_pk_mul_f32 v[206:207], v[16:17], v[88:89]
	v_pk_fma_f32 v[212:213], v[18:19], v[98:99], v[212:213]
	v_pk_fma_f32 v[216:217], v[10:11], v[98:99], v[216:217]
	v_pk_fma_f32 v[212:213], v[20:21], v[100:101], v[212:213]
	v_pk_fma_f32 v[216:217], v[12:13], v[100:101], v[216:217]
	v_add_f32_e32 v226, v222, v223
	v_add_f32_e32 v227, v224, v225
	v_add_f32_e32 v220, v212, v213
	v_add_f32_e32 v221, v216, v217
	v_pk_mul_f32 v[200:201], v[18:19], v[90:91]
	v_pk_mul_f32 v[208:209], v[10:11], v[90:91]
	ds_write_b64 v228, v[226:227] offset:7488
	v_add_f32_dpp v220, v220, v220 quad_perm:[1,0,3,2] row_mask:0xf bank_mask:0xf bound_ctrl:1
	v_add_f32_dpp v221, v221, v221 quad_perm:[1,0,3,2] row_mask:0xf bank_mask:0xf bound_ctrl:1
	v_pk_mul_f32 v[202:203], v[20:21], v[92:93]
	v_pk_mul_f32 v[210:211], v[12:13], v[92:93]
	v_add_f32_dpp v220, v220, v220 quad_perm:[2,3,0,1] row_mask:0xf bank_mask:0xf bound_ctrl:1
	v_add_f32_dpp v221, v221, v221 quad_perm:[2,3,0,1] row_mask:0xf bank_mask:0xf bound_ctrl:1
	s_nop 0
	v_add_f32_dpp v220, v220, v220 row_half_mirror row_mask:0xf bank_mask:0xf bound_ctrl:1
	v_add_f32_dpp v221, v221, v221 row_half_mirror row_mask:0xf bank_mask:0xf bound_ctrl:1
	s_nop 0
	v_pk_fma_f32 v[22:23], v[220:221], v[102:103], v[196:197] op_sel_hi:[0,1,1] neg_lo:[1,0,0] neg_hi:[1,0,0]
	v_pk_fma_f32 v[14:15], v[220:221], v[102:103], v[204:205] op_sel:[1,0,0] op_sel_hi:[1,1,1] neg_lo:[1,0,0] neg_hi:[1,0,0]
	v_pk_fma_f32 v[24:25], v[220:221], v[104:105], v[198:199] op_sel_hi:[0,1,1] neg_lo:[1,0,0] neg_hi:[1,0,0]
	v_pk_fma_f32 v[16:17], v[220:221], v[104:105], v[206:207] op_sel:[1,0,0] op_sel_hi:[1,1,1] neg_lo:[1,0,0] neg_hi:[1,0,0]
	v_pk_fma_f32 v[18:19], v[220:221], v[106:107], v[200:201] op_sel_hi:[0,1,1] neg_lo:[1,0,0] neg_hi:[1,0,0]
	v_pk_fma_f32 v[10:11], v[220:221], v[106:107], v[208:209] op_sel:[1,0,0] op_sel_hi:[1,1,1] neg_lo:[1,0,0] neg_hi:[1,0,0]
	v_pk_fma_f32 v[20:21], v[220:221], v[108:109], v[202:203] op_sel_hi:[0,1,1] neg_lo:[1,0,0] neg_hi:[1,0,0]
	v_pk_fma_f32 v[12:13], v[220:221], v[108:109], v[210:211] op_sel:[1,0,0] op_sel_hi:[1,1,1] neg_lo:[1,0,0] neg_hi:[1,0,0]
	v_pk_mul_f32 v[222:223], v[22:23], v[118:119]
	v_pk_mul_f32 v[224:225], v[14:15], v[118:119]
	v_pk_fma_f32 v[222:223], v[24:25], v[120:121], v[222:223]
	v_pk_fma_f32 v[224:225], v[16:17], v[120:121], v[224:225]
	v_pk_fma_f32 v[222:223], v[18:19], v[122:123], v[222:223]
	v_pk_fma_f32 v[224:225], v[10:11], v[122:123], v[224:225]
	v_pk_fma_f32 v[222:223], v[20:21], v[124:125], v[222:223]
	v_pk_fma_f32 v[224:225], v[12:13], v[124:125], v[224:225]
	s_waitcnt lgkmcnt(0)
	v_pk_mul_f32 v[212:213], v[22:23], v[136:137]
	v_pk_mul_f32 v[216:217], v[14:15], v[136:137]
	v_pk_mul_f32 v[196:197], v[22:23], v[128:129]
	v_pk_mul_f32 v[204:205], v[14:15], v[128:129]
	v_pk_fma_f32 v[212:213], v[24:25], v[138:139], v[212:213]
	v_pk_fma_f32 v[216:217], v[16:17], v[138:139], v[216:217]
	v_pk_mul_f32 v[198:199], v[24:25], v[130:131]
	v_pk_mul_f32 v[206:207], v[16:17], v[130:131]
	v_pk_fma_f32 v[212:213], v[18:19], v[140:141], v[212:213]
	v_pk_fma_f32 v[216:217], v[10:11], v[140:141], v[216:217]
	v_pk_fma_f32 v[212:213], v[20:21], v[142:143], v[212:213]
	v_pk_fma_f32 v[216:217], v[12:13], v[142:143], v[216:217]
	v_add_f32_e32 v226, v222, v223
	v_add_f32_e32 v227, v224, v225
	v_add_f32_e32 v220, v212, v213
	v_add_f32_e32 v221, v216, v217
	v_pk_mul_f32 v[200:201], v[18:19], v[132:133]
	v_pk_mul_f32 v[208:209], v[10:11], v[132:133]
	ds_write_b64 v228, v[226:227] offset:8064
	v_add_f32_dpp v220, v220, v220 quad_perm:[1,0,3,2] row_mask:0xf bank_mask:0xf bound_ctrl:1
	v_add_f32_dpp v221, v221, v221 quad_perm:[1,0,3,2] row_mask:0xf bank_mask:0xf bound_ctrl:1
	v_pk_mul_f32 v[202:203], v[20:21], v[134:135]
	v_pk_mul_f32 v[210:211], v[12:13], v[134:135]
	v_add_f32_dpp v220, v220, v220 quad_perm:[2,3,0,1] row_mask:0xf bank_mask:0xf bound_ctrl:1
	v_add_f32_dpp v221, v221, v221 quad_perm:[2,3,0,1] row_mask:0xf bank_mask:0xf bound_ctrl:1
	s_nop 0
	v_add_f32_dpp v220, v220, v220 row_half_mirror row_mask:0xf bank_mask:0xf bound_ctrl:1
	v_add_f32_dpp v221, v221, v221 row_half_mirror row_mask:0xf bank_mask:0xf bound_ctrl:1
	s_nop 0
	v_pk_fma_f32 v[22:23], v[220:221], v[144:145], v[196:197] op_sel_hi:[0,1,1] neg_lo:[1,0,0] neg_hi:[1,0,0]
	v_pk_fma_f32 v[14:15], v[220:221], v[144:145], v[204:205] op_sel:[1,0,0] op_sel_hi:[1,1,1] neg_lo:[1,0,0] neg_hi:[1,0,0]
	v_pk_fma_f32 v[24:25], v[220:221], v[146:147], v[198:199] op_sel_hi:[0,1,1] neg_lo:[1,0,0] neg_hi:[1,0,0]
	v_pk_fma_f32 v[16:17], v[220:221], v[146:147], v[206:207] op_sel:[1,0,0] op_sel_hi:[1,1,1] neg_lo:[1,0,0] neg_hi:[1,0,0]
	v_pk_fma_f32 v[18:19], v[220:221], v[148:149], v[200:201] op_sel_hi:[0,1,1] neg_lo:[1,0,0] neg_hi:[1,0,0]
	v_pk_fma_f32 v[10:11], v[220:221], v[148:149], v[208:209] op_sel:[1,0,0] op_sel_hi:[1,1,1] neg_lo:[1,0,0] neg_hi:[1,0,0]
	v_pk_fma_f32 v[20:21], v[220:221], v[150:151], v[202:203] op_sel_hi:[0,1,1] neg_lo:[1,0,0] neg_hi:[1,0,0]
	v_pk_fma_f32 v[12:13], v[220:221], v[150:151], v[210:211] op_sel:[1,0,0] op_sel_hi:[1,1,1] neg_lo:[1,0,0] neg_hi:[1,0,0]
	v_pk_mul_f32 v[222:223], v[22:23], v[160:161]
	v_pk_mul_f32 v[224:225], v[14:15], v[160:161]
	v_pk_fma_f32 v[222:223], v[24:25], v[162:163], v[222:223]
	v_pk_fma_f32 v[224:225], v[16:17], v[162:163], v[224:225]
	v_pk_fma_f32 v[222:223], v[18:19], v[164:165], v[222:223]
	v_pk_fma_f32 v[224:225], v[10:11], v[164:165], v[224:225]
	v_pk_fma_f32 v[222:223], v[20:21], v[166:167], v[222:223]
	v_pk_fma_f32 v[224:225], v[12:13], v[166:167], v[224:225]
	v_add_f32_e32 v226, v222, v223
	v_add_f32_e32 v227, v224, v225
	ds_write_b64 v228, v[226:227] offset:8640
	s_setprio 0
